# prologue gain loads hoisted ahead of the weight tile loads; mixer_b rewritten by hand: all loads up front, LN rows batched with DPP/permlane all-reduce
# speedup vs baseline: 1.0186x; 1.0186x over previous
.LBB0_29:
	s_mul_hi_i32 s12, s24, 0x2e8ba2e9
	s_lshr_b32 s13, s12, 31
	s_ashr_i32 s25, s12, 4
	s_add_i32 s25, s25, s13
	s_mul_i32 s13, s25, 0xffffea00
	s_add_i32 s14, s16, s13
	s_lshl_b32 s12, s25, 6
	v_add_u32_e32 v80, s12, v82
	s_ashr_i32 s15, s14, 31
	v_lshl_add_u64 v[40:41], s[14:15], 2, v[64:65]
	v_add_u32_e32 v50, 56, v80
	v_add_u32_e32 v2, 4, v80
	v_add_u32_e32 v8, 8, v80
	v_add_u32_e32 v10, 12, v80
	v_add_u32_e32 v16, 16, v80
	v_add_u32_e32 v18, 20, v80
	v_add_u32_e32 v24, 24, v80
	v_add_u32_e32 v26, 28, v80
	v_add_u32_e32 v32, 32, v80
	v_add_u32_e32 v34, 36, v80
	v_add_u32_e32 v42, 40, v80
	v_add_u32_e32 v44, 44, v80
	v_add_u32_e32 v46, 48, v80
	v_add_u32_e32 v48, 52, v80
	v_mad_i64_i32 v[116:117], s[26:27], v50, s18, v[40:41]
	v_add_u32_e32 v50, 60, v80
	v_mad_i64_i32 v[0:1], s[26:27], v80, s18, v[40:41]
	v_mad_i64_i32 v[2:3], s[26:27], v2, s18, v[40:41]
	v_mad_i64_i32 v[8:9], s[26:27], v8, s18, v[40:41]
	v_mad_i64_i32 v[10:11], s[26:27], v10, s18, v[40:41]
	v_mad_i64_i32 v[16:17], s[26:27], v16, s18, v[40:41]
	v_mad_i64_i32 v[18:19], s[26:27], v18, s18, v[40:41]
	v_mad_i64_i32 v[24:25], s[26:27], v24, s18, v[40:41]
	v_mad_i64_i32 v[26:27], s[26:27], v26, s18, v[40:41]
	v_mad_i64_i32 v[32:33], s[26:27], v32, s18, v[40:41]
	v_mad_i64_i32 v[34:35], s[26:27], v34, s18, v[40:41]
	v_mad_i64_i32 v[42:43], s[26:27], v42, s18, v[40:41]
	v_mad_i64_i32 v[44:45], s[26:27], v44, s18, v[40:41]
	v_mad_i64_i32 v[46:47], s[26:27], v46, s18, v[40:41]
	v_mad_i64_i32 v[48:49], s[26:27], v48, s18, v[40:41]
	v_mad_i64_i32 v[40:41], s[26:27], v50, s18, v[40:41]
	s_andn2_b64 vcc, exec, s[4:5]
	s_cbranch_vccnz .Lgk1_nold
	s_load_dwordx16 s[48:63], s[0:1], 0x0
	v_ashrrev_i32_e32 v81, 31, v80
	s_waitcnt lgkmcnt(0)
	v_lshl_add_u64 v[80:81], v[80:81], 2, s[52:53]
	global_load_dword v126, v[80:81], off
	global_load_dword v128, v[80:81], off offset:16
	global_load_dword v130, v[80:81], off offset:32
	global_load_dword v132, v[80:81], off offset:48
	global_load_dword v134, v[80:81], off offset:64
	global_load_dword v136, v[80:81], off offset:80
	global_load_dword v138, v[80:81], off offset:96
	global_load_dword v140, v[80:81], off offset:112
	global_load_dword v142, v[80:81], off offset:128
	global_load_dword v144, v[80:81], off offset:144
	global_load_dword v146, v[80:81], off offset:160
	global_load_dword v148, v[80:81], off offset:176
	global_load_dword v150, v[80:81], off offset:192
	global_load_dword v152, v[80:81], off offset:208
	global_load_dword v154, v[80:81], off offset:224
	global_load_dword v156, v[80:81], off offset:240
.Lgk1_nold:
	global_load_dwordx4 v[4:7], v[0:1], off
	s_nop 0
	global_load_dwordx4 v[0:3], v[2:3], off
	s_nop 0
	global_load_dwordx4 v[12:15], v[8:9], off
	s_nop 0
	global_load_dwordx4 v[8:11], v[10:11], off
	s_nop 0
	global_load_dwordx4 v[20:23], v[16:17], off
	s_nop 0
	global_load_dwordx4 v[16:19], v[18:19], off
	s_nop 0
	global_load_dwordx4 v[28:31], v[24:25], off
	s_nop 0
	global_load_dwordx4 v[24:27], v[26:27], off
	s_nop 0
	global_load_dwordx4 v[36:39], v[32:33], off
	s_nop 0
	global_load_dwordx4 v[32:35], v[34:35], off
	s_nop 0
	global_load_dwordx4 v[60:63], v[42:43], off
	global_load_dwordx4 v[56:59], v[44:45], off
	global_load_dwordx4 v[52:55], v[46:47], off
	s_nop 0
	global_load_dwordx4 v[48:51], v[48:49], off
	s_nop 0
	global_load_dwordx4 v[44:47], v[116:117], off
	s_nop 0
	global_load_dwordx4 v[40:43], v[40:41], off
	s_andn2_b64 vcc, exec, s[4:5]
	s_cbranch_vccnz .LBB0_31
	s_waitcnt vmcnt(15)
	v_pk_mul_f32 v[6:7], v[6:7], v[126:127] op_sel_hi:[1,0]
	v_pk_mul_f32 v[4:5], v[4:5], v[126:127] op_sel_hi:[1,0]
	s_waitcnt vmcnt(14)
	v_pk_mul_f32 v[2:3], v[2:3], v[128:129] op_sel_hi:[1,0]
	v_pk_mul_f32 v[0:1], v[0:1], v[128:129] op_sel_hi:[1,0]
	s_waitcnt vmcnt(13)
	v_pk_mul_f32 v[14:15], v[14:15], v[130:131] op_sel_hi:[1,0]
	v_pk_mul_f32 v[12:13], v[12:13], v[130:131] op_sel_hi:[1,0]
	s_waitcnt vmcnt(12)
	v_pk_mul_f32 v[10:11], v[10:11], v[132:133] op_sel_hi:[1,0]
	v_pk_mul_f32 v[8:9], v[8:9], v[132:133] op_sel_hi:[1,0]
	s_waitcnt vmcnt(11)
	v_pk_mul_f32 v[22:23], v[22:23], v[134:135] op_sel_hi:[1,0]
	v_pk_mul_f32 v[20:21], v[20:21], v[134:135] op_sel_hi:[1,0]
	s_waitcnt vmcnt(10)
	v_pk_mul_f32 v[18:19], v[18:19], v[136:137] op_sel_hi:[1,0]
	v_pk_mul_f32 v[16:17], v[16:17], v[136:137] op_sel_hi:[1,0]
	s_waitcnt vmcnt(9)
	v_pk_mul_f32 v[30:31], v[30:31], v[138:139] op_sel_hi:[1,0]
	v_pk_mul_f32 v[28:29], v[28:29], v[138:139] op_sel_hi:[1,0]
	s_waitcnt vmcnt(8)
	v_pk_mul_f32 v[26:27], v[26:27], v[140:141] op_sel_hi:[1,0]
	v_pk_mul_f32 v[24:25], v[24:25], v[140:141] op_sel_hi:[1,0]
	s_waitcnt vmcnt(7)
	v_pk_mul_f32 v[38:39], v[38:39], v[142:143] op_sel_hi:[1,0]
	v_pk_mul_f32 v[36:37], v[36:37], v[142:143] op_sel_hi:[1,0]
	s_waitcnt vmcnt(6)
	v_pk_mul_f32 v[34:35], v[34:35], v[144:145] op_sel_hi:[1,0]
	v_pk_mul_f32 v[32:33], v[32:33], v[144:145] op_sel_hi:[1,0]
	s_waitcnt vmcnt(5)
	v_pk_mul_f32 v[62:63], v[62:63], v[146:147] op_sel_hi:[1,0]
	v_pk_mul_f32 v[60:61], v[60:61], v[146:147] op_sel_hi:[1,0]
	s_waitcnt vmcnt(4)
	v_pk_mul_f32 v[58:59], v[58:59], v[148:149] op_sel_hi:[1,0]
	v_pk_mul_f32 v[56:57], v[56:57], v[148:149] op_sel_hi:[1,0]
	s_waitcnt vmcnt(3)
	v_pk_mul_f32 v[54:55], v[54:55], v[150:151] op_sel_hi:[1,0]
	v_pk_mul_f32 v[52:53], v[52:53], v[150:151] op_sel_hi:[1,0]
	s_waitcnt vmcnt(2)
	v_pk_mul_f32 v[50:51], v[50:51], v[152:153] op_sel_hi:[1,0]
	v_pk_mul_f32 v[48:49], v[48:49], v[152:153] op_sel_hi:[1,0]
	s_waitcnt vmcnt(1)
	v_pk_mul_f32 v[46:47], v[46:47], v[154:155] op_sel_hi:[1,0]
	v_pk_mul_f32 v[44:45], v[44:45], v[154:155] op_sel_hi:[1,0]
	s_waitcnt vmcnt(0)
	v_pk_mul_f32 v[42:43], v[42:43], v[156:157] op_sel_hi:[1,0]
	v_pk_mul_f32 v[40:41], v[40:41], v[156:157] op_sel_hi:[1,0]

.LBB0_41:
	s_cmpk_lt_i32 s26, 0x200
	s_cselect_b64 s[12:13], -1, 0
	s_and_b64 s[10:11], s[10:11], s[12:13]
	s_andn2_b64 vcc, exec, s[10:11]
	s_cbranch_vccnz .LBB0_24
	s_ashr_i32 s10, s26, 31
	s_lshr_b32 s10, s10, 27
	s_add_i32 s11, s26, s10
	s_and_b32 s10, s11, 0x3ffffe0
	s_lshl_b32 s11, s11, 1
	s_and_b32 s12, s11, 0xffffffc0
	s_sub_i32 s10, s26, s10
	v_add_u32_e32 v80, s12, v82
	s_lshl_b32 s10, s10, 6
	v_add_u32_e32 v2, 4, v80
	v_add_u32_e32 v8, 8, v80
	v_add_u32_e32 v10, 12, v80
	v_add_u32_e32 v16, 16, v80
	v_add_u32_e32 v18, 20, v80
	v_add_u32_e32 v24, 24, v80
	v_add_u32_e32 v26, 28, v80
	v_add_u32_e32 v32, 32, v80
	v_add_u32_e32 v34, 36, v80
	v_add_u32_e32 v40, 40, v80
	v_add_u32_e32 v42, 44, v80
	v_add_u32_e32 v48, 48, v80
	v_add_u32_e32 v50, 52, v80
	v_add_u32_e32 v58, 56, v80
	v_add_u32_e32 v60, 60, v80
	s_ashr_i32 s11, s10, 31
	v_ashrrev_i32_e32 v81, 31, v80
	v_ashrrev_i32_e32 v3, 31, v2
	v_ashrrev_i32_e32 v9, 31, v8
	v_ashrrev_i32_e32 v11, 31, v10
	v_ashrrev_i32_e32 v17, 31, v16
	v_ashrrev_i32_e32 v19, 31, v18
	v_ashrrev_i32_e32 v25, 31, v24
	v_ashrrev_i32_e32 v27, 31, v26
	v_ashrrev_i32_e32 v33, 31, v32
	v_ashrrev_i32_e32 v35, 31, v34
	v_ashrrev_i32_e32 v41, 31, v40
	v_ashrrev_i32_e32 v43, 31, v42
	v_ashrrev_i32_e32 v49, 31, v48
	v_ashrrev_i32_e32 v51, 31, v50
	v_ashrrev_i32_e32 v59, 31, v58
	v_ashrrev_i32_e32 v61, 31, v60
	v_lshl_add_u64 v[56:57], s[10:11], 2, v[72:73]
	v_lshlrev_b64 v[0:1], 13, v[80:81]
	v_lshlrev_b64 v[2:3], 13, v[2:3]
	v_lshlrev_b64 v[8:9], 13, v[8:9]
	v_lshlrev_b64 v[10:11], 13, v[10:11]
	v_lshlrev_b64 v[16:17], 13, v[16:17]
	v_lshlrev_b64 v[18:19], 13, v[18:19]
	v_lshlrev_b64 v[24:25], 13, v[24:25]
	v_lshlrev_b64 v[26:27], 13, v[26:27]
	v_lshlrev_b64 v[32:33], 13, v[32:33]
	v_lshlrev_b64 v[34:35], 13, v[34:35]
	v_lshlrev_b64 v[40:41], 13, v[40:41]
	v_lshlrev_b64 v[42:43], 13, v[42:43]
	v_lshlrev_b64 v[48:49], 13, v[48:49]
	v_lshlrev_b64 v[50:51], 13, v[50:51]
	v_lshlrev_b64 v[58:59], 13, v[58:59]
	v_lshlrev_b64 v[60:61], 13, v[60:61]
	v_lshl_add_u64 v[0:1], v[56:57], 0, v[0:1]
	v_lshl_add_u64 v[2:3], v[56:57], 0, v[2:3]
	v_lshl_add_u64 v[8:9], v[56:57], 0, v[8:9]
	v_lshl_add_u64 v[10:11], v[56:57], 0, v[10:11]
	v_lshl_add_u64 v[16:17], v[56:57], 0, v[16:17]
	v_lshl_add_u64 v[18:19], v[56:57], 0, v[18:19]
	v_lshl_add_u64 v[24:25], v[56:57], 0, v[24:25]
	v_lshl_add_u64 v[26:27], v[56:57], 0, v[26:27]
	v_lshl_add_u64 v[32:33], v[56:57], 0, v[32:33]
	v_lshl_add_u64 v[34:35], v[56:57], 0, v[34:35]
	v_lshl_add_u64 v[40:41], v[56:57], 0, v[40:41]
	v_lshl_add_u64 v[42:43], v[56:57], 0, v[42:43]
	v_lshl_add_u64 v[48:49], v[56:57], 0, v[48:49]
	v_lshl_add_u64 v[50:51], v[56:57], 0, v[50:51]
	v_lshl_add_u64 v[58:59], v[56:57], 0, v[58:59]
	v_lshl_add_u64 v[56:57], v[56:57], 0, v[60:61]
	s_andn2_b64 vcc, exec, s[6:7]
	s_cbranch_vccnz .Lgk2_nold
	s_load_dwordx16 s[48:63], s[0:1], 0x0
	s_waitcnt lgkmcnt(0)
	v_lshl_add_u64 v[80:81], v[80:81], 2, s[58:59]
	global_load_dword v126, v[80:81], off
	global_load_dword v128, v[80:81], off offset:16
	global_load_dword v130, v[80:81], off offset:32
	global_load_dword v132, v[80:81], off offset:48
	global_load_dword v134, v[80:81], off offset:64
	global_load_dword v136, v[80:81], off offset:80
	global_load_dword v138, v[80:81], off offset:96
	global_load_dword v140, v[80:81], off offset:112
	global_load_dword v142, v[80:81], off offset:128
	global_load_dword v144, v[80:81], off offset:144
	global_load_dword v146, v[80:81], off offset:160
	global_load_dword v148, v[80:81], off offset:176
	global_load_dword v150, v[80:81], off offset:192
	global_load_dword v152, v[80:81], off offset:208
	global_load_dword v154, v[80:81], off offset:224
	global_load_dword v156, v[80:81], off offset:240
.Lgk2_nold:
	global_load_dwordx4 v[4:7], v[0:1], off
	s_nop 0
	global_load_dwordx4 v[0:3], v[2:3], off
	s_nop 0
	global_load_dwordx4 v[12:15], v[8:9], off
	s_nop 0
	global_load_dwordx4 v[8:11], v[10:11], off
	s_nop 0
	global_load_dwordx4 v[20:23], v[16:17], off
	s_nop 0
	global_load_dwordx4 v[16:19], v[18:19], off
	s_nop 0
	global_load_dwordx4 v[28:31], v[24:25], off
	s_nop 0
	global_load_dwordx4 v[24:27], v[26:27], off
	s_nop 0
	global_load_dwordx4 v[36:39], v[32:33], off
	s_nop 0
	global_load_dwordx4 v[32:35], v[34:35], off
	s_nop 0
	global_load_dwordx4 v[44:47], v[40:41], off
	s_nop 0
	global_load_dwordx4 v[40:43], v[42:43], off
	s_nop 0
	global_load_dwordx4 v[52:55], v[48:49], off
	s_nop 0
	global_load_dwordx4 v[48:51], v[50:51], off
	s_nop 0
	global_load_dwordx4 v[60:63], v[58:59], off
	s_nop 0
	global_load_dwordx4 v[56:59], v[56:57], off
	s_andn2_b64 vcc, exec, s[6:7]
	s_cbranch_vccnz .LBB0_23
	s_waitcnt vmcnt(15)
	v_pk_mul_f32 v[6:7], v[6:7], v[126:127] op_sel_hi:[1,0]
	v_pk_mul_f32 v[4:5], v[4:5], v[126:127] op_sel_hi:[1,0]
	s_waitcnt vmcnt(14)
	v_pk_mul_f32 v[2:3], v[2:3], v[128:129] op_sel_hi:[1,0]
	v_pk_mul_f32 v[0:1], v[0:1], v[128:129] op_sel_hi:[1,0]
	s_waitcnt vmcnt(13)
	v_pk_mul_f32 v[14:15], v[14:15], v[130:131] op_sel_hi:[1,0]
	v_pk_mul_f32 v[12:13], v[12:13], v[130:131] op_sel_hi:[1,0]
	s_waitcnt vmcnt(12)
	v_pk_mul_f32 v[10:11], v[10:11], v[132:133] op_sel_hi:[1,0]
	v_pk_mul_f32 v[8:9], v[8:9], v[132:133] op_sel_hi:[1,0]
	s_waitcnt vmcnt(11)
	v_pk_mul_f32 v[22:23], v[22:23], v[134:135] op_sel_hi:[1,0]
	v_pk_mul_f32 v[20:21], v[20:21], v[134:135] op_sel_hi:[1,0]
	s_waitcnt vmcnt(10)
	v_pk_mul_f32 v[18:19], v[18:19], v[136:137] op_sel_hi:[1,0]
	v_pk_mul_f32 v[16:17], v[16:17], v[136:137] op_sel_hi:[1,0]
	s_waitcnt vmcnt(9)
	v_pk_mul_f32 v[30:31], v[30:31], v[138:139] op_sel_hi:[1,0]
	v_pk_mul_f32 v[28:29], v[28:29], v[138:139] op_sel_hi:[1,0]
	s_waitcnt vmcnt(8)
	v_pk_mul_f32 v[26:27], v[26:27], v[140:141] op_sel_hi:[1,0]
	v_pk_mul_f32 v[24:25], v[24:25], v[140:141] op_sel_hi:[1,0]
	s_waitcnt vmcnt(7)
	v_pk_mul_f32 v[38:39], v[38:39], v[142:143] op_sel_hi:[1,0]
	v_pk_mul_f32 v[36:37], v[36:37], v[142:143] op_sel_hi:[1,0]
	s_waitcnt vmcnt(6)
	v_pk_mul_f32 v[34:35], v[34:35], v[144:145] op_sel_hi:[1,0]
	v_pk_mul_f32 v[32:33], v[32:33], v[144:145] op_sel_hi:[1,0]
	s_waitcnt vmcnt(5)
	v_pk_mul_f32 v[46:47], v[46:47], v[146:147] op_sel_hi:[1,0]
	v_pk_mul_f32 v[44:45], v[44:45], v[146:147] op_sel_hi:[1,0]
	s_waitcnt vmcnt(4)
	v_pk_mul_f32 v[42:43], v[42:43], v[148:149] op_sel_hi:[1,0]
	v_pk_mul_f32 v[40:41], v[40:41], v[148:149] op_sel_hi:[1,0]
	s_waitcnt vmcnt(3)
	v_pk_mul_f32 v[54:55], v[54:55], v[150:151] op_sel_hi:[1,0]
	v_pk_mul_f32 v[52:53], v[52:53], v[150:151] op_sel_hi:[1,0]
	s_waitcnt vmcnt(2)
	v_pk_mul_f32 v[50:51], v[50:51], v[152:153] op_sel_hi:[1,0]
	v_pk_mul_f32 v[48:49], v[48:49], v[152:153] op_sel_hi:[1,0]
	s_waitcnt vmcnt(1)
	v_pk_mul_f32 v[62:63], v[62:63], v[154:155] op_sel_hi:[1,0]
	v_pk_mul_f32 v[60:61], v[60:61], v[154:155] op_sel_hi:[1,0]
	s_waitcnt vmcnt(0)
	v_pk_mul_f32 v[58:59], v[58:59], v[156:157] op_sel_hi:[1,0]
	v_pk_mul_f32 v[56:57], v[56:57], v[156:157] op_sel_hi:[1,0]
	s_branch .LBB0_23

.LBB0_477:
	s_mov_b64 s[4:5], 0
	s_and_b64 vcc, exec, s[2:3]
	s_mov_b64 s[2:3], 0
	s_cbranch_vccz .LBB0_485
	v_writelane_b32 v255, s8, 40
	v_writelane_b32 v255, s9, 41
	v_writelane_b32 v255, s10, 42
	v_writelane_b32 v255, s11, 43
	v_writelane_b32 v255, s12, 44
	v_writelane_b32 v255, s13, 45
	v_writelane_b32 v255, s14, 46
	v_writelane_b32 v255, s15, 47
	s_lshl_b32 s0, s18, 7
	s_add_i32 s0, s0, 0xffff0000
	v_lshrrev_b32_e32 v9, 6, v176
	v_and_b32_e32 v0, 15, v197
	v_readfirstlane_b32 s2, v9
	v_lshrrev_b32_e32 v1, 4, v197
	v_lshlrev_b32_e32 v2, 3, v197
	v_lshlrev_b32_e32 v9, 4, v197
	s_nop 3
	s_lshr_b32 s3, s2, 1
	s_and_b32 s4, s2, 1
	s_lshl_b32 s5, s2, 4
	s_add_i32 s5, s5, s0
	s_mul_i32 s5, s5, 0x1800
	s_add_u32 s8, s66, s5
	s_addc_u32 s9, s67, 0
	global_load_dwordx2 v[32:33], v2, s[8:9] offset:2048
	s_add_u32 s8, s8, 0x1800
	s_addc_u32 s9, s9, 0
	global_load_dwordx2 v[34:35], v2, s[8:9] offset:2048
	s_add_u32 s8, s8, 0x1800
	s_addc_u32 s9, s9, 0
	global_load_dwordx2 v[36:37], v2, s[8:9] offset:2048
	s_add_u32 s8, s8, 0x1800
	s_addc_u32 s9, s9, 0
	global_load_dwordx2 v[38:39], v2, s[8:9] offset:2048
	s_add_u32 s8, s8, 0x1800
	s_addc_u32 s9, s9, 0
	global_load_dwordx2 v[40:41], v2, s[8:9] offset:2048
	s_add_u32 s8, s8, 0x1800
	s_addc_u32 s9, s9, 0
	global_load_dwordx2 v[42:43], v2, s[8:9] offset:2048
	s_add_u32 s8, s8, 0x1800
	s_addc_u32 s9, s9, 0
	global_load_dwordx2 v[44:45], v2, s[8:9] offset:2048
	s_add_u32 s8, s8, 0x1800
	s_addc_u32 s9, s9, 0
	global_load_dwordx2 v[46:47], v2, s[8:9] offset:2048
	s_add_u32 s8, s8, 0x1800
	s_addc_u32 s9, s9, 0
	global_load_dwordx2 v[48:49], v2, s[8:9] offset:2048
	s_add_u32 s8, s8, 0x1800
	s_addc_u32 s9, s9, 0
	global_load_dwordx2 v[50:51], v2, s[8:9] offset:2048
	s_add_u32 s8, s8, 0x1800
	s_addc_u32 s9, s9, 0
	global_load_dwordx2 v[52:53], v2, s[8:9] offset:2048
	s_add_u32 s8, s8, 0x1800
	s_addc_u32 s9, s9, 0
	global_load_dwordx2 v[54:55], v2, s[8:9] offset:2048
	s_add_u32 s8, s8, 0x1800
	s_addc_u32 s9, s9, 0
	global_load_dwordx2 v[56:57], v2, s[8:9] offset:2048
	s_add_u32 s8, s8, 0x1800
	s_addc_u32 s9, s9, 0
	global_load_dwordx2 v[58:59], v2, s[8:9] offset:2048
	s_add_u32 s8, s8, 0x1800
	s_addc_u32 s9, s9, 0
	global_load_dwordx2 v[60:61], v2, s[8:9] offset:2048
	s_add_u32 s8, s8, 0x1800
	s_addc_u32 s9, s9, 0
	global_load_dwordx2 v[62:63], v2, s[8:9] offset:2048
	global_load_dwordx4 v[10:13], v9, s[40:41]
	s_lshl_b32 s5, s3, 7
	s_lshl_b32 s36, s4, 6
	s_add_i32 s5, s5, s36
	s_lshl_b32 s36, s5, 2
	s_add_u32 s14, s44, s36
	s_addc_u32 s15, s45, 0
	s_lshl_b32 s5, s5, 9
	s_add_u32 s10, s42, s5
	s_addc_u32 s11, s43, 0
	v_lshlrev_b32_e32 v3, 9, v0
	v_lshl_add_u32 v3, v1, 5, v3
	global_load_dwordx4 v[64:67], v3, s[10:11]
	global_load_dwordx4 v[68:71], v3, s[10:11] offset:16
	global_load_dwordx4 v[96:99], v3, s[10:11] offset:128
	global_load_dwordx4 v[100:103], v3, s[10:11] offset:144
	s_add_u32 s10, s10, 0x2000
	s_addc_u32 s11, s11, 0
	global_load_dwordx4 v[72:75], v3, s[10:11]
	global_load_dwordx4 v[76:79], v3, s[10:11] offset:16
	global_load_dwordx4 v[104:107], v3, s[10:11] offset:128
	global_load_dwordx4 v[108:111], v3, s[10:11] offset:144
	s_add_u32 s10, s10, 0x2000
	s_addc_u32 s11, s11, 0
	global_load_dwordx4 v[80:83], v3, s[10:11]
	global_load_dwordx4 v[84:87], v3, s[10:11] offset:16
	global_load_dwordx4 v[112:115], v3, s[10:11] offset:128
	global_load_dwordx4 v[116:119], v3, s[10:11] offset:144
	s_add_u32 s10, s10, 0x2000
	s_addc_u32 s11, s11, 0
	global_load_dwordx4 v[88:91], v3, s[10:11]
	global_load_dwordx4 v[92:95], v3, s[10:11] offset:16
	global_load_dwordx4 v[120:123], v3, s[10:11] offset:128
	global_load_dwordx4 v[124:127], v3, s[10:11] offset:144
	s_add_u32 s10, s10, 0x2000
	s_addc_u32 s11, s11, 0
	s_sub_u32 s12, 0, s4
	s_mov_b32 s13, 0xf800000
	v_mul_u32_u24_e32 v4, 0x440, v197
	s_lshl_b32 s5, s2, 5
	v_add_u32_e32 v4, s5, v4
	v_mul_u32_u24_e32 v5, 0x110, v0
	v_lshl_add_u32 v5, v1, 4, v5
	s_mul_i32 s5, s3, 0x4400
	v_add_u32_e32 v5, s5, v5
	v_mul_u32_u24_e32 v6, 0x1800, v0
	v_lshl_add_u32 v6, v1, 3, v6
	v_lshlrev_b32_e32 v7, 2, v0
	v_mov_b32_e32 v8, 0xffff
	v_lshlrev_b32_e32 v130, 3, v1
	v_sub_u32_e32 v128, v0, v130
	v_add_u32_e32 v129, 16, v128
	v_add_u32_e32 v130, 0, v128
	v_add_u32_e32 v131, -1, v130
	v_ashrrev_i32_e32 v130, 31, v130
	v_ashrrev_i32_e32 v131, 31, v131
	v_not_b32_e32 v130, v130
	v_not_b32_e32 v131, v131
	v_bfi_b32 v14, v8, v130, v131
	v_add_u32_e32 v130, -2, v128
	v_add_u32_e32 v131, -1, v130
	v_ashrrev_i32_e32 v130, 31, v130
	v_ashrrev_i32_e32 v131, 31, v131
	v_not_b32_e32 v130, v130
	v_not_b32_e32 v131, v131
	v_bfi_b32 v15, v8, v130, v131
	v_add_u32_e32 v130, -4, v128
	v_add_u32_e32 v131, -1, v130
	v_ashrrev_i32_e32 v130, 31, v130
	v_ashrrev_i32_e32 v131, 31, v131
	v_not_b32_e32 v130, v130
	v_not_b32_e32 v131, v131
	v_bfi_b32 v16, v8, v130, v131
	v_add_u32_e32 v130, -6, v128
	v_add_u32_e32 v131, -1, v130
	v_ashrrev_i32_e32 v130, 31, v130
	v_ashrrev_i32_e32 v131, 31, v131
	v_not_b32_e32 v130, v130
	v_not_b32_e32 v131, v131
	v_bfi_b32 v17, v8, v130, v131
	v_add_u32_e32 v130, 0, v129
	v_add_u32_e32 v131, -1, v130
	v_ashrrev_i32_e32 v130, 31, v130
	v_ashrrev_i32_e32 v131, 31, v131
	v_not_b32_e32 v130, v130
	v_not_b32_e32 v131, v131
	v_bfi_b32 v18, v8, v130, v131
	v_add_u32_e32 v130, -2, v129
	v_add_u32_e32 v131, -1, v130
	v_ashrrev_i32_e32 v130, 31, v130
	v_ashrrev_i32_e32 v131, 31, v131
	v_not_b32_e32 v130, v130
	v_not_b32_e32 v131, v131
	v_bfi_b32 v19, v8, v130, v131
	v_add_u32_e32 v130, -4, v129
	v_add_u32_e32 v131, -1, v130
	v_ashrrev_i32_e32 v130, 31, v130
	v_ashrrev_i32_e32 v131, 31, v131
	v_not_b32_e32 v130, v130
	v_not_b32_e32 v131, v131
	v_bfi_b32 v20, v8, v130, v131
	v_add_u32_e32 v130, -6, v129
	v_add_u32_e32 v131, -1, v130
	v_ashrrev_i32_e32 v130, 31, v130
	v_ashrrev_i32_e32 v131, 31, v131
	v_not_b32_e32 v130, v130
	v_not_b32_e32 v131, v131
	v_bfi_b32 v21, v8, v130, v131
	v_or_b32_e32 v22, s12, v14
	v_or_b32_e32 v23, s12, v15
	v_or_b32_e32 v24, s12, v16
	v_or_b32_e32 v25, s12, v17
	v_or_b32_e32 v26, s12, v18
	v_or_b32_e32 v27, s12, v19
	v_or_b32_e32 v28, s12, v20
	v_or_b32_e32 v29, s12, v21
	s_waitcnt vmcnt(16)
	v_lshlrev_b32_e32 v128, 16, v32
	v_and_b32_e32 v129, 0xffff0000, v32
	v_lshlrev_b32_e32 v130, 16, v33
	v_and_b32_e32 v131, 0xffff0000, v33
	v_lshlrev_b32_e32 v132, 16, v34
	v_and_b32_e32 v133, 0xffff0000, v34
	v_lshlrev_b32_e32 v134, 16, v35
	v_and_b32_e32 v135, 0xffff0000, v35
	v_lshlrev_b32_e32 v136, 16, v36
	v_and_b32_e32 v137, 0xffff0000, v36
	v_lshlrev_b32_e32 v138, 16, v37
	v_and_b32_e32 v139, 0xffff0000, v37
	v_lshlrev_b32_e32 v140, 16, v38
	v_and_b32_e32 v141, 0xffff0000, v38
	v_lshlrev_b32_e32 v142, 16, v39
	v_and_b32_e32 v143, 0xffff0000, v39
	v_add_f32_e32 v156, v128, v129
	v_add_f32_e32 v160, v130, v131
	v_add_f32_e32 v157, v132, v133
	v_add_f32_e32 v161, v134, v135
	v_add_f32_e32 v158, v136, v137
	v_add_f32_e32 v162, v138, v139
	v_add_f32_e32 v159, v140, v141
	v_add_f32_e32 v163, v142, v143
	v_add_f32_e32 v156, v156, v160
	v_add_f32_e32 v157, v157, v161
	v_add_f32_e32 v158, v158, v162
	v_add_f32_e32 v159, v159, v163
	v_add_f32_dpp v156, v156, v156 quad_perm:[1,0,3,2] row_mask:0xf bank_mask:0xf
	v_add_f32_dpp v157, v157, v157 quad_perm:[1,0,3,2] row_mask:0xf bank_mask:0xf
	v_add_f32_dpp v158, v158, v158 quad_perm:[1,0,3,2] row_mask:0xf bank_mask:0xf
	v_add_f32_dpp v159, v159, v159 quad_perm:[1,0,3,2] row_mask:0xf bank_mask:0xf
	v_add_f32_dpp v156, v156, v156 quad_perm:[2,3,0,1] row_mask:0xf bank_mask:0xf
	v_add_f32_dpp v157, v157, v157 quad_perm:[2,3,0,1] row_mask:0xf bank_mask:0xf
	v_add_f32_dpp v158, v158, v158 quad_perm:[2,3,0,1] row_mask:0xf bank_mask:0xf
	v_add_f32_dpp v159, v159, v159 quad_perm:[2,3,0,1] row_mask:0xf bank_mask:0xf
	v_add_f32_dpp v156, v156, v156 row_half_mirror row_mask:0xf bank_mask:0xf
	v_add_f32_dpp v157, v157, v157 row_half_mirror row_mask:0xf bank_mask:0xf
	v_add_f32_dpp v158, v158, v158 row_half_mirror row_mask:0xf bank_mask:0xf
	v_add_f32_dpp v159, v159, v159 row_half_mirror row_mask:0xf bank_mask:0xf
	v_add_f32_dpp v156, v156, v156 row_mirror row_mask:0xf bank_mask:0xf
	v_add_f32_dpp v157, v157, v157 row_mirror row_mask:0xf bank_mask:0xf
	v_add_f32_dpp v158, v158, v158 row_mirror row_mask:0xf bank_mask:0xf
	v_add_f32_dpp v159, v159, v159 row_mirror row_mask:0xf bank_mask:0xf
	v_mov_b32_e32 v160, v156
	v_mov_b32_e32 v161, v157
	v_mov_b32_e32 v162, v158
	v_mov_b32_e32 v163, v159
	v_permlane16_swap_b32_e32 v156, v160
	v_permlane16_swap_b32_e32 v157, v161
	v_permlane16_swap_b32_e32 v158, v162
	v_permlane16_swap_b32_e32 v159, v163
	v_add_f32_e32 v156, v156, v160
	v_add_f32_e32 v157, v157, v161
	v_add_f32_e32 v158, v158, v162
	v_add_f32_e32 v159, v159, v163
	v_mov_b32_e32 v160, v156
	v_mov_b32_e32 v161, v157
	v_mov_b32_e32 v162, v158
	v_mov_b32_e32 v163, v159
	v_permlane32_swap_b32_e32 v156, v160
	v_permlane32_swap_b32_e32 v157, v161
	v_permlane32_swap_b32_e32 v158, v162
	v_permlane32_swap_b32_e32 v159, v163
	v_add_f32_e32 v156, v156, v160
	v_add_f32_e32 v157, v157, v161
	v_add_f32_e32 v158, v158, v162
	v_add_f32_e32 v159, v159, v163
	v_fmac_f32_e32 v129, 0xbb800000, v156
	v_fmac_f32_e32 v131, 0xbb800000, v156
	v_fmac_f32_e32 v130, 0xbb800000, v156
	v_fmac_f32_e32 v128, 0xbb800000, v156
	v_fmac_f32_e32 v133, 0xbb800000, v157
	v_fmac_f32_e32 v135, 0xbb800000, v157
	v_fmac_f32_e32 v134, 0xbb800000, v157
	v_fmac_f32_e32 v132, 0xbb800000, v157
	v_fmac_f32_e32 v137, 0xbb800000, v158
	v_fmac_f32_e32 v139, 0xbb800000, v158
	v_fmac_f32_e32 v138, 0xbb800000, v158
	v_fmac_f32_e32 v136, 0xbb800000, v158
	v_fmac_f32_e32 v141, 0xbb800000, v159
	v_fmac_f32_e32 v143, 0xbb800000, v159
	v_fmac_f32_e32 v142, 0xbb800000, v159
	v_fmac_f32_e32 v140, 0xbb800000, v159
	v_mul_f32_e32 v156, v128, v128
	v_mul_f32_e32 v160, v129, v129
	v_mul_f32_e32 v164, v130, v130
	v_mul_f32_e32 v168, v131, v131
	v_mul_f32_e32 v157, v132, v132
	v_mul_f32_e32 v161, v133, v133
	v_mul_f32_e32 v165, v134, v134
	v_mul_f32_e32 v169, v135, v135
	v_mul_f32_e32 v158, v136, v136
	v_mul_f32_e32 v162, v137, v137
	v_mul_f32_e32 v166, v138, v138
	v_mul_f32_e32 v170, v139, v139
	v_mul_f32_e32 v159, v140, v140
	v_mul_f32_e32 v163, v141, v141
	v_mul_f32_e32 v167, v142, v142
	v_mul_f32_e32 v171, v143, v143
	v_add_f32_e32 v156, v160, v156
	v_add_f32_e32 v164, v164, v168
	v_add_f32_e32 v157, v161, v157
	v_add_f32_e32 v165, v165, v169
	v_add_f32_e32 v158, v162, v158
	v_add_f32_e32 v166, v166, v170
	v_add_f32_e32 v159, v163, v159
	v_add_f32_e32 v167, v167, v171
	v_add_f32_e32 v156, v156, v164
	v_add_f32_e32 v157, v157, v165
	v_add_f32_e32 v158, v158, v166
	v_add_f32_e32 v159, v159, v167
	v_add_f32_dpp v156, v156, v156 quad_perm:[1,0,3,2] row_mask:0xf bank_mask:0xf
	v_add_f32_dpp v157, v157, v157 quad_perm:[1,0,3,2] row_mask:0xf bank_mask:0xf
	v_add_f32_dpp v158, v158, v158 quad_perm:[1,0,3,2] row_mask:0xf bank_mask:0xf
	v_add_f32_dpp v159, v159, v159 quad_perm:[1,0,3,2] row_mask:0xf bank_mask:0xf
	v_add_f32_dpp v156, v156, v156 quad_perm:[2,3,0,1] row_mask:0xf bank_mask:0xf
	v_add_f32_dpp v157, v157, v157 quad_perm:[2,3,0,1] row_mask:0xf bank_mask:0xf
	v_add_f32_dpp v158, v158, v158 quad_perm:[2,3,0,1] row_mask:0xf bank_mask:0xf
	v_add_f32_dpp v159, v159, v159 quad_perm:[2,3,0,1] row_mask:0xf bank_mask:0xf
	v_add_f32_dpp v156, v156, v156 row_half_mirror row_mask:0xf bank_mask:0xf
	v_add_f32_dpp v157, v157, v157 row_half_mirror row_mask:0xf bank_mask:0xf
	v_add_f32_dpp v158, v158, v158 row_half_mirror row_mask:0xf bank_mask:0xf
	v_add_f32_dpp v159, v159, v159 row_half_mirror row_mask:0xf bank_mask:0xf
	v_add_f32_dpp v156, v156, v156 row_mirror row_mask:0xf bank_mask:0xf
	v_add_f32_dpp v157, v157, v157 row_mirror row_mask:0xf bank_mask:0xf
	v_add_f32_dpp v158, v158, v158 row_mirror row_mask:0xf bank_mask:0xf
	v_add_f32_dpp v159, v159, v159 row_mirror row_mask:0xf bank_mask:0xf
	v_mov_b32_e32 v160, v156
	v_mov_b32_e32 v161, v157
	v_mov_b32_e32 v162, v158
	v_mov_b32_e32 v163, v159
	v_permlane16_swap_b32_e32 v156, v160
	v_permlane16_swap_b32_e32 v157, v161
	v_permlane16_swap_b32_e32 v158, v162
	v_permlane16_swap_b32_e32 v159, v163
	v_add_f32_e32 v156, v156, v160
	v_add_f32_e32 v157, v157, v161
	v_add_f32_e32 v158, v158, v162
	v_add_f32_e32 v159, v159, v163
	v_mov_b32_e32 v160, v156
	v_mov_b32_e32 v161, v157
	v_mov_b32_e32 v162, v158
	v_mov_b32_e32 v163, v159
	v_permlane32_swap_b32_e32 v156, v160
	v_permlane32_swap_b32_e32 v157, v161
	v_permlane32_swap_b32_e32 v158, v162
	v_permlane32_swap_b32_e32 v159, v163
	v_add_f32_e32 v156, v156, v160
	v_add_f32_e32 v157, v157, v161
	v_add_f32_e32 v158, v158, v162
	v_add_f32_e32 v159, v159, v163
	v_fmamk_f32 v156, v156, 0x3b800000, v194
	v_fmamk_f32 v157, v157, 0x3b800000, v194
	v_fmamk_f32 v158, v158, 0x3b800000, v194
	v_fmamk_f32 v159, v159, 0x3b800000, v194
	v_cmp_gt_f32_e32 vcc, s13, v156
	v_mul_f32_e32 v164, 0x4f800000, v156
	s_nop 0
	v_cndmask_b32_e32 v156, v156, v164, vcc
	v_sqrt_f32_e32 v164, v156
	s_nop 0
	v_add_u32_e32 v165, -1, v164
	v_fma_f32 v166, -v165, v164, v156
	v_cmp_ge_f32_e64 s[36:37], 0, v166
	v_add_u32_e32 v166, 1, v164
	s_nop 0
	v_cndmask_b32_e64 v165, v164, v165, s[36:37]
	v_fma_f32 v164, -v166, v164, v156
	v_cmp_lt_f32_e64 s[36:37], 0, v164
	s_nop 1
	v_cndmask_b32_e64 v164, v165, v166, s[36:37]
	v_mul_f32_e32 v165, 0x37800000, v164
	v_cndmask_b32_e32 v164, v164, v165, vcc
	v_cmp_class_f32_e32 vcc, v156, v196
	s_nop 1
	v_cndmask_b32_e32 v156, v164, v156, vcc
	v_div_scale_f32 v164, s[36:37], v156, v156, 1.0
	v_rcp_f32_e32 v165, v164
	s_nop 0
	v_fma_f32 v166, -v164, v165, 1.0
	v_fmac_f32_e32 v165, v166, v165
	v_div_scale_f32 v166, vcc, 1.0, v156, 1.0
	v_mul_f32_e32 v167, v166, v165
	v_fma_f32 v168, -v164, v167, v166
	v_fmac_f32_e32 v167, v168, v165
	v_fma_f32 v164, -v164, v167, v166
	v_div_fmas_f32 v164, v164, v165, v167
	v_div_fixup_f32 v156, v164, v156, 1.0
	v_cmp_gt_f32_e32 vcc, s13, v157
	v_mul_f32_e32 v164, 0x4f800000, v157
	s_nop 0
	v_cndmask_b32_e32 v157, v157, v164, vcc
	v_sqrt_f32_e32 v164, v157
	s_nop 0
	v_add_u32_e32 v165, -1, v164
	v_fma_f32 v166, -v165, v164, v157
	v_cmp_ge_f32_e64 s[36:37], 0, v166
	v_add_u32_e32 v166, 1, v164
	s_nop 0
	v_cndmask_b32_e64 v165, v164, v165, s[36:37]
	v_fma_f32 v164, -v166, v164, v157
	v_cmp_lt_f32_e64 s[36:37], 0, v164
	s_nop 1
	v_cndmask_b32_e64 v164, v165, v166, s[36:37]
	v_mul_f32_e32 v165, 0x37800000, v164
	v_cndmask_b32_e32 v164, v164, v165, vcc
	v_cmp_class_f32_e32 vcc, v157, v196
	s_nop 1
	v_cndmask_b32_e32 v157, v164, v157, vcc
	v_div_scale_f32 v164, s[36:37], v157, v157, 1.0
	v_rcp_f32_e32 v165, v164
	s_nop 0
	v_fma_f32 v166, -v164, v165, 1.0
	v_fmac_f32_e32 v165, v166, v165
	v_div_scale_f32 v166, vcc, 1.0, v157, 1.0
	v_mul_f32_e32 v167, v166, v165
	v_fma_f32 v168, -v164, v167, v166
	v_fmac_f32_e32 v167, v168, v165
	v_fma_f32 v164, -v164, v167, v166
	v_div_fmas_f32 v164, v164, v165, v167
	v_div_fixup_f32 v157, v164, v157, 1.0
	v_cmp_gt_f32_e32 vcc, s13, v158
	v_mul_f32_e32 v164, 0x4f800000, v158
	s_nop 0
	v_cndmask_b32_e32 v158, v158, v164, vcc
	v_sqrt_f32_e32 v164, v158
	s_nop 0
	v_add_u32_e32 v165, -1, v164
	v_fma_f32 v166, -v165, v164, v158
	v_cmp_ge_f32_e64 s[36:37], 0, v166
	v_add_u32_e32 v166, 1, v164
	s_nop 0
	v_cndmask_b32_e64 v165, v164, v165, s[36:37]
	v_fma_f32 v164, -v166, v164, v158
	v_cmp_lt_f32_e64 s[36:37], 0, v164
	s_nop 1
	v_cndmask_b32_e64 v164, v165, v166, s[36:37]
	v_mul_f32_e32 v165, 0x37800000, v164
	v_cndmask_b32_e32 v164, v164, v165, vcc
	v_cmp_class_f32_e32 vcc, v158, v196
	s_nop 1
	v_cndmask_b32_e32 v158, v164, v158, vcc
	v_div_scale_f32 v164, s[36:37], v158, v158, 1.0
	v_rcp_f32_e32 v165, v164
	s_nop 0
	v_fma_f32 v166, -v164, v165, 1.0
	v_fmac_f32_e32 v165, v166, v165
	v_div_scale_f32 v166, vcc, 1.0, v158, 1.0
	v_mul_f32_e32 v167, v166, v165
	v_fma_f32 v168, -v164, v167, v166
	v_fmac_f32_e32 v167, v168, v165
	v_fma_f32 v164, -v164, v167, v166
	v_div_fmas_f32 v164, v164, v165, v167
	v_div_fixup_f32 v158, v164, v158, 1.0
	v_cmp_gt_f32_e32 vcc, s13, v159
	v_mul_f32_e32 v164, 0x4f800000, v159
	s_nop 0
	v_cndmask_b32_e32 v159, v159, v164, vcc
	v_sqrt_f32_e32 v164, v159
	s_nop 0
	v_add_u32_e32 v165, -1, v164
	v_fma_f32 v166, -v165, v164, v159
	v_cmp_ge_f32_e64 s[36:37], 0, v166
	v_add_u32_e32 v166, 1, v164
	s_nop 0
	v_cndmask_b32_e64 v165, v164, v165, s[36:37]
	v_fma_f32 v164, -v166, v164, v159
	v_cmp_lt_f32_e64 s[36:37], 0, v164
	s_nop 1
	v_cndmask_b32_e64 v164, v165, v166, s[36:37]
	v_mul_f32_e32 v165, 0x37800000, v164
	v_cndmask_b32_e32 v164, v164, v165, vcc
	v_cmp_class_f32_e32 vcc, v159, v196
	s_nop 1
	v_cndmask_b32_e32 v159, v164, v159, vcc
	v_div_scale_f32 v164, s[36:37], v159, v159, 1.0
	v_rcp_f32_e32 v165, v164
	s_nop 0
	v_fma_f32 v166, -v164, v165, 1.0
	v_fmac_f32_e32 v165, v166, v165
	v_div_scale_f32 v166, vcc, 1.0, v159, 1.0
	v_mul_f32_e32 v167, v166, v165
	v_fma_f32 v168, -v164, v167, v166
	v_fmac_f32_e32 v167, v168, v165
	v_fma_f32 v164, -v164, v167, v166
	v_div_fmas_f32 v164, v164, v165, v167
	v_div_fixup_f32 v159, v164, v159, 1.0
	v_mul_f32_e32 v128, v128, v156
	v_mul_f32_e32 v129, v129, v156
	v_mul_f32_e32 v130, v130, v156
	v_mul_f32_e32 v131, v131, v156
	v_mul_f32_e32 v132, v132, v157
	v_mul_f32_e32 v133, v133, v157
	v_mul_f32_e32 v134, v134, v157
	v_mul_f32_e32 v135, v135, v157
	v_mul_f32_e32 v136, v136, v158
	v_mul_f32_e32 v137, v137, v158
	v_mul_f32_e32 v138, v138, v158
	v_mul_f32_e32 v139, v139, v158
	v_mul_f32_e32 v140, v140, v159
	v_mul_f32_e32 v141, v141, v159
	v_mul_f32_e32 v142, v142, v159
	v_mul_f32_e32 v143, v143, v159
	v_mul_f32_e32 v128, v10, v128
	v_mul_f32_e32 v129, v11, v129
	v_mul_f32_e32 v130, v12, v130
	v_mul_f32_e32 v131, v13, v131
	v_mul_f32_e32 v132, v10, v132
	v_mul_f32_e32 v133, v11, v133
	v_mul_f32_e32 v134, v12, v134
	v_mul_f32_e32 v135, v13, v135
	v_mul_f32_e32 v136, v10, v136
	v_mul_f32_e32 v137, v11, v137
	v_mul_f32_e32 v138, v12, v138
	v_mul_f32_e32 v139, v13, v139
	v_mul_f32_e32 v140, v10, v140
	v_mul_f32_e32 v141, v11, v141
	v_mul_f32_e32 v142, v12, v142
	v_mul_f32_e32 v143, v13, v143
	v_cvt_pk_bf16_f32 v172, v128, v132
	v_cvt_pk_bf16_f32 v173, v136, v140
	v_cvt_pk_bf16_f32 v174, v129, v133
	v_cvt_pk_bf16_f32 v175, v137, v141
	v_cvt_pk_bf16_f32 v146, v130, v134
	v_cvt_pk_bf16_f32 v147, v138, v142
	v_cvt_pk_bf16_f32 v154, v131, v135
	v_cvt_pk_bf16_f32 v155, v139, v143
	ds_write_b64 v4, v[172:173] offset:0
	ds_write_b64 v4, v[174:175] offset:272
	ds_write_b64 v4, v[146:147] offset:544
	ds_write_b64 v4, v[154:155] offset:816
	v_lshlrev_b32_e32 v128, 16, v40
	v_and_b32_e32 v129, 0xffff0000, v40
	v_lshlrev_b32_e32 v130, 16, v41
	v_and_b32_e32 v131, 0xffff0000, v41
	v_lshlrev_b32_e32 v132, 16, v42
	v_and_b32_e32 v133, 0xffff0000, v42
	v_lshlrev_b32_e32 v134, 16, v43
	v_and_b32_e32 v135, 0xffff0000, v43
	v_lshlrev_b32_e32 v136, 16, v44
	v_and_b32_e32 v137, 0xffff0000, v44
	v_lshlrev_b32_e32 v138, 16, v45
	v_and_b32_e32 v139, 0xffff0000, v45
	v_lshlrev_b32_e32 v140, 16, v46
	v_and_b32_e32 v141, 0xffff0000, v46
	v_lshlrev_b32_e32 v142, 16, v47
	v_and_b32_e32 v143, 0xffff0000, v47
	v_add_f32_e32 v156, v128, v129
	v_add_f32_e32 v160, v130, v131
	v_add_f32_e32 v157, v132, v133
	v_add_f32_e32 v161, v134, v135
	v_add_f32_e32 v158, v136, v137
	v_add_f32_e32 v162, v138, v139
	v_add_f32_e32 v159, v140, v141
	v_add_f32_e32 v163, v142, v143
	v_add_f32_e32 v156, v156, v160
	v_add_f32_e32 v157, v157, v161
	v_add_f32_e32 v158, v158, v162
	v_add_f32_e32 v159, v159, v163
	v_add_f32_dpp v156, v156, v156 quad_perm:[1,0,3,2] row_mask:0xf bank_mask:0xf
	v_add_f32_dpp v157, v157, v157 quad_perm:[1,0,3,2] row_mask:0xf bank_mask:0xf
	v_add_f32_dpp v158, v158, v158 quad_perm:[1,0,3,2] row_mask:0xf bank_mask:0xf
	v_add_f32_dpp v159, v159, v159 quad_perm:[1,0,3,2] row_mask:0xf bank_mask:0xf
	v_add_f32_dpp v156, v156, v156 quad_perm:[2,3,0,1] row_mask:0xf bank_mask:0xf
	v_add_f32_dpp v157, v157, v157 quad_perm:[2,3,0,1] row_mask:0xf bank_mask:0xf
	v_add_f32_dpp v158, v158, v158 quad_perm:[2,3,0,1] row_mask:0xf bank_mask:0xf
	v_add_f32_dpp v159, v159, v159 quad_perm:[2,3,0,1] row_mask:0xf bank_mask:0xf
	v_add_f32_dpp v156, v156, v156 row_half_mirror row_mask:0xf bank_mask:0xf
	v_add_f32_dpp v157, v157, v157 row_half_mirror row_mask:0xf bank_mask:0xf
	v_add_f32_dpp v158, v158, v158 row_half_mirror row_mask:0xf bank_mask:0xf
	v_add_f32_dpp v159, v159, v159 row_half_mirror row_mask:0xf bank_mask:0xf
	v_add_f32_dpp v156, v156, v156 row_mirror row_mask:0xf bank_mask:0xf
	v_add_f32_dpp v157, v157, v157 row_mirror row_mask:0xf bank_mask:0xf
	v_add_f32_dpp v158, v158, v158 row_mirror row_mask:0xf bank_mask:0xf
	v_add_f32_dpp v159, v159, v159 row_mirror row_mask:0xf bank_mask:0xf
	v_mov_b32_e32 v160, v156
	v_mov_b32_e32 v161, v157
	v_mov_b32_e32 v162, v158
	v_mov_b32_e32 v163, v159
	v_permlane16_swap_b32_e32 v156, v160
	v_permlane16_swap_b32_e32 v157, v161
	v_permlane16_swap_b32_e32 v158, v162
	v_permlane16_swap_b32_e32 v159, v163
	v_add_f32_e32 v156, v156, v160
	v_add_f32_e32 v157, v157, v161
	v_add_f32_e32 v158, v158, v162
	v_add_f32_e32 v159, v159, v163
	v_mov_b32_e32 v160, v156
	v_mov_b32_e32 v161, v157
	v_mov_b32_e32 v162, v158
	v_mov_b32_e32 v163, v159
	v_permlane32_swap_b32_e32 v156, v160
	v_permlane32_swap_b32_e32 v157, v161
	v_permlane32_swap_b32_e32 v158, v162
	v_permlane32_swap_b32_e32 v159, v163
	v_add_f32_e32 v156, v156, v160
	v_add_f32_e32 v157, v157, v161
	v_add_f32_e32 v158, v158, v162
	v_add_f32_e32 v159, v159, v163
	v_fmac_f32_e32 v129, 0xbb800000, v156
	v_fmac_f32_e32 v131, 0xbb800000, v156
	v_fmac_f32_e32 v130, 0xbb800000, v156
	v_fmac_f32_e32 v128, 0xbb800000, v156
	v_fmac_f32_e32 v133, 0xbb800000, v157
	v_fmac_f32_e32 v135, 0xbb800000, v157
	v_fmac_f32_e32 v134, 0xbb800000, v157
	v_fmac_f32_e32 v132, 0xbb800000, v157
	v_fmac_f32_e32 v137, 0xbb800000, v158
	v_fmac_f32_e32 v139, 0xbb800000, v158
	v_fmac_f32_e32 v138, 0xbb800000, v158
	v_fmac_f32_e32 v136, 0xbb800000, v158
	v_fmac_f32_e32 v141, 0xbb800000, v159
	v_fmac_f32_e32 v143, 0xbb800000, v159
	v_fmac_f32_e32 v142, 0xbb800000, v159
	v_fmac_f32_e32 v140, 0xbb800000, v159
	v_mul_f32_e32 v156, v128, v128
	v_mul_f32_e32 v160, v129, v129
	v_mul_f32_e32 v164, v130, v130
	v_mul_f32_e32 v168, v131, v131
	v_mul_f32_e32 v157, v132, v132
	v_mul_f32_e32 v161, v133, v133
	v_mul_f32_e32 v165, v134, v134
	v_mul_f32_e32 v169, v135, v135
	v_mul_f32_e32 v158, v136, v136
	v_mul_f32_e32 v162, v137, v137
	v_mul_f32_e32 v166, v138, v138
	v_mul_f32_e32 v170, v139, v139
	v_mul_f32_e32 v159, v140, v140
	v_mul_f32_e32 v163, v141, v141
	v_mul_f32_e32 v167, v142, v142
	v_mul_f32_e32 v171, v143, v143
	v_add_f32_e32 v156, v160, v156
	v_add_f32_e32 v164, v164, v168
	v_add_f32_e32 v157, v161, v157
	v_add_f32_e32 v165, v165, v169
	v_add_f32_e32 v158, v162, v158
	v_add_f32_e32 v166, v166, v170
	v_add_f32_e32 v159, v163, v159
	v_add_f32_e32 v167, v167, v171
	v_add_f32_e32 v156, v156, v164
	v_add_f32_e32 v157, v157, v165
	v_add_f32_e32 v158, v158, v166
	v_add_f32_e32 v159, v159, v167
	v_add_f32_dpp v156, v156, v156 quad_perm:[1,0,3,2] row_mask:0xf bank_mask:0xf
	v_add_f32_dpp v157, v157, v157 quad_perm:[1,0,3,2] row_mask:0xf bank_mask:0xf
	v_add_f32_dpp v158, v158, v158 quad_perm:[1,0,3,2] row_mask:0xf bank_mask:0xf
	v_add_f32_dpp v159, v159, v159 quad_perm:[1,0,3,2] row_mask:0xf bank_mask:0xf
	v_add_f32_dpp v156, v156, v156 quad_perm:[2,3,0,1] row_mask:0xf bank_mask:0xf
	v_add_f32_dpp v157, v157, v157 quad_perm:[2,3,0,1] row_mask:0xf bank_mask:0xf
	v_add_f32_dpp v158, v158, v158 quad_perm:[2,3,0,1] row_mask:0xf bank_mask:0xf
	v_add_f32_dpp v159, v159, v159 quad_perm:[2,3,0,1] row_mask:0xf bank_mask:0xf
	v_add_f32_dpp v156, v156, v156 row_half_mirror row_mask:0xf bank_mask:0xf
	v_add_f32_dpp v157, v157, v157 row_half_mirror row_mask:0xf bank_mask:0xf
	v_add_f32_dpp v158, v158, v158 row_half_mirror row_mask:0xf bank_mask:0xf
	v_add_f32_dpp v159, v159, v159 row_half_mirror row_mask:0xf bank_mask:0xf
	v_add_f32_dpp v156, v156, v156 row_mirror row_mask:0xf bank_mask:0xf
	v_add_f32_dpp v157, v157, v157 row_mirror row_mask:0xf bank_mask:0xf
	v_add_f32_dpp v158, v158, v158 row_mirror row_mask:0xf bank_mask:0xf
	v_add_f32_dpp v159, v159, v159 row_mirror row_mask:0xf bank_mask:0xf
	v_mov_b32_e32 v160, v156
	v_mov_b32_e32 v161, v157
	v_mov_b32_e32 v162, v158
	v_mov_b32_e32 v163, v159
	v_permlane16_swap_b32_e32 v156, v160
	v_permlane16_swap_b32_e32 v157, v161
	v_permlane16_swap_b32_e32 v158, v162
	v_permlane16_swap_b32_e32 v159, v163
	v_add_f32_e32 v156, v156, v160
	v_add_f32_e32 v157, v157, v161
	v_add_f32_e32 v158, v158, v162
	v_add_f32_e32 v159, v159, v163
	v_mov_b32_e32 v160, v156
	v_mov_b32_e32 v161, v157
	v_mov_b32_e32 v162, v158
	v_mov_b32_e32 v163, v159
	v_permlane32_swap_b32_e32 v156, v160
	v_permlane32_swap_b32_e32 v157, v161
	v_permlane32_swap_b32_e32 v158, v162
	v_permlane32_swap_b32_e32 v159, v163
	v_add_f32_e32 v156, v156, v160
	v_add_f32_e32 v157, v157, v161
	v_add_f32_e32 v158, v158, v162
	v_add_f32_e32 v159, v159, v163
	v_fmamk_f32 v156, v156, 0x3b800000, v194
	v_fmamk_f32 v157, v157, 0x3b800000, v194
	v_fmamk_f32 v158, v158, 0x3b800000, v194
	v_fmamk_f32 v159, v159, 0x3b800000, v194
	v_cmp_gt_f32_e32 vcc, s13, v156
	v_mul_f32_e32 v164, 0x4f800000, v156
	s_nop 0
	v_cndmask_b32_e32 v156, v156, v164, vcc
	v_sqrt_f32_e32 v164, v156
	s_nop 0
	v_add_u32_e32 v165, -1, v164
	v_fma_f32 v166, -v165, v164, v156
	v_cmp_ge_f32_e64 s[36:37], 0, v166
	v_add_u32_e32 v166, 1, v164
	s_nop 0
	v_cndmask_b32_e64 v165, v164, v165, s[36:37]
	v_fma_f32 v164, -v166, v164, v156
	v_cmp_lt_f32_e64 s[36:37], 0, v164
	s_nop 1
	v_cndmask_b32_e64 v164, v165, v166, s[36:37]
	v_mul_f32_e32 v165, 0x37800000, v164
	v_cndmask_b32_e32 v164, v164, v165, vcc
	v_cmp_class_f32_e32 vcc, v156, v196
	s_nop 1
	v_cndmask_b32_e32 v156, v164, v156, vcc
	v_div_scale_f32 v164, s[36:37], v156, v156, 1.0
	v_rcp_f32_e32 v165, v164
	s_nop 0
	v_fma_f32 v166, -v164, v165, 1.0
	v_fmac_f32_e32 v165, v166, v165
	v_div_scale_f32 v166, vcc, 1.0, v156, 1.0
	v_mul_f32_e32 v167, v166, v165
	v_fma_f32 v168, -v164, v167, v166
	v_fmac_f32_e32 v167, v168, v165
	v_fma_f32 v164, -v164, v167, v166
	v_div_fmas_f32 v164, v164, v165, v167
	v_div_fixup_f32 v156, v164, v156, 1.0
	v_cmp_gt_f32_e32 vcc, s13, v157
	v_mul_f32_e32 v164, 0x4f800000, v157
	s_nop 0
	v_cndmask_b32_e32 v157, v157, v164, vcc
	v_sqrt_f32_e32 v164, v157
	s_nop 0
	v_add_u32_e32 v165, -1, v164
	v_fma_f32 v166, -v165, v164, v157
	v_cmp_ge_f32_e64 s[36:37], 0, v166
	v_add_u32_e32 v166, 1, v164
	s_nop 0
	v_cndmask_b32_e64 v165, v164, v165, s[36:37]
	v_fma_f32 v164, -v166, v164, v157
	v_cmp_lt_f32_e64 s[36:37], 0, v164
	s_nop 1
	v_cndmask_b32_e64 v164, v165, v166, s[36:37]
	v_mul_f32_e32 v165, 0x37800000, v164
	v_cndmask_b32_e32 v164, v164, v165, vcc
	v_cmp_class_f32_e32 vcc, v157, v196
	s_nop 1
	v_cndmask_b32_e32 v157, v164, v157, vcc
	v_div_scale_f32 v164, s[36:37], v157, v157, 1.0
	v_rcp_f32_e32 v165, v164
	s_nop 0
	v_fma_f32 v166, -v164, v165, 1.0
	v_fmac_f32_e32 v165, v166, v165
	v_div_scale_f32 v166, vcc, 1.0, v157, 1.0
	v_mul_f32_e32 v167, v166, v165
	v_fma_f32 v168, -v164, v167, v166
	v_fmac_f32_e32 v167, v168, v165
	v_fma_f32 v164, -v164, v167, v166
	v_div_fmas_f32 v164, v164, v165, v167
	v_div_fixup_f32 v157, v164, v157, 1.0
	v_cmp_gt_f32_e32 vcc, s13, v158
	v_mul_f32_e32 v164, 0x4f800000, v158
	s_nop 0
	v_cndmask_b32_e32 v158, v158, v164, vcc
	v_sqrt_f32_e32 v164, v158
	s_nop 0
	v_add_u32_e32 v165, -1, v164
	v_fma_f32 v166, -v165, v164, v158
	v_cmp_ge_f32_e64 s[36:37], 0, v166
	v_add_u32_e32 v166, 1, v164
	s_nop 0
	v_cndmask_b32_e64 v165, v164, v165, s[36:37]
	v_fma_f32 v164, -v166, v164, v158
	v_cmp_lt_f32_e64 s[36:37], 0, v164
	s_nop 1
	v_cndmask_b32_e64 v164, v165, v166, s[36:37]
	v_mul_f32_e32 v165, 0x37800000, v164
	v_cndmask_b32_e32 v164, v164, v165, vcc
	v_cmp_class_f32_e32 vcc, v158, v196
	s_nop 1
	v_cndmask_b32_e32 v158, v164, v158, vcc
	v_div_scale_f32 v164, s[36:37], v158, v158, 1.0
	v_rcp_f32_e32 v165, v164
	s_nop 0
	v_fma_f32 v166, -v164, v165, 1.0
	v_fmac_f32_e32 v165, v166, v165
	v_div_scale_f32 v166, vcc, 1.0, v158, 1.0
	v_mul_f32_e32 v167, v166, v165
	v_fma_f32 v168, -v164, v167, v166
	v_fmac_f32_e32 v167, v168, v165
	v_fma_f32 v164, -v164, v167, v166
	v_div_fmas_f32 v164, v164, v165, v167
	v_div_fixup_f32 v158, v164, v158, 1.0
	v_cmp_gt_f32_e32 vcc, s13, v159
	v_mul_f32_e32 v164, 0x4f800000, v159
	s_nop 0
	v_cndmask_b32_e32 v159, v159, v164, vcc
	v_sqrt_f32_e32 v164, v159
	s_nop 0
	v_add_u32_e32 v165, -1, v164
	v_fma_f32 v166, -v165, v164, v159
	v_cmp_ge_f32_e64 s[36:37], 0, v166
	v_add_u32_e32 v166, 1, v164
	s_nop 0
	v_cndmask_b32_e64 v165, v164, v165, s[36:37]
	v_fma_f32 v164, -v166, v164, v159
	v_cmp_lt_f32_e64 s[36:37], 0, v164
	s_nop 1
	v_cndmask_b32_e64 v164, v165, v166, s[36:37]
	v_mul_f32_e32 v165, 0x37800000, v164
	v_cndmask_b32_e32 v164, v164, v165, vcc
	v_cmp_class_f32_e32 vcc, v159, v196
	s_nop 1
	v_cndmask_b32_e32 v159, v164, v159, vcc
	v_div_scale_f32 v164, s[36:37], v159, v159, 1.0
	v_rcp_f32_e32 v165, v164
	s_nop 0
	v_fma_f32 v166, -v164, v165, 1.0
	v_fmac_f32_e32 v165, v166, v165
	v_div_scale_f32 v166, vcc, 1.0, v159, 1.0
	v_mul_f32_e32 v167, v166, v165
	v_fma_f32 v168, -v164, v167, v166
	v_fmac_f32_e32 v167, v168, v165
	v_fma_f32 v164, -v164, v167, v166
	v_div_fmas_f32 v164, v164, v165, v167
	v_div_fixup_f32 v159, v164, v159, 1.0
	v_mul_f32_e32 v128, v128, v156
	v_mul_f32_e32 v129, v129, v156
	v_mul_f32_e32 v130, v130, v156
	v_mul_f32_e32 v131, v131, v156
	v_mul_f32_e32 v132, v132, v157
	v_mul_f32_e32 v133, v133, v157
	v_mul_f32_e32 v134, v134, v157
	v_mul_f32_e32 v135, v135, v157
	v_mul_f32_e32 v136, v136, v158
	v_mul_f32_e32 v137, v137, v158
	v_mul_f32_e32 v138, v138, v158
	v_mul_f32_e32 v139, v139, v158
	v_mul_f32_e32 v140, v140, v159
	v_mul_f32_e32 v141, v141, v159
	v_mul_f32_e32 v142, v142, v159
	v_mul_f32_e32 v143, v143, v159
	v_mul_f32_e32 v128, v10, v128
	v_mul_f32_e32 v129, v11, v129
	v_mul_f32_e32 v130, v12, v130
	v_mul_f32_e32 v131, v13, v131
	v_mul_f32_e32 v132, v10, v132
	v_mul_f32_e32 v133, v11, v133
	v_mul_f32_e32 v134, v12, v134
	v_mul_f32_e32 v135, v13, v135
	v_mul_f32_e32 v136, v10, v136
	v_mul_f32_e32 v137, v11, v137
	v_mul_f32_e32 v138, v12, v138
	v_mul_f32_e32 v139, v13, v139
	v_mul_f32_e32 v140, v10, v140
	v_mul_f32_e32 v141, v11, v141
	v_mul_f32_e32 v142, v12, v142
	v_mul_f32_e32 v143, v13, v143
	v_cvt_pk_bf16_f32 v172, v128, v132
	v_cvt_pk_bf16_f32 v173, v136, v140
	v_cvt_pk_bf16_f32 v174, v129, v133
	v_cvt_pk_bf16_f32 v175, v137, v141
	v_cvt_pk_bf16_f32 v146, v130, v134
	v_cvt_pk_bf16_f32 v147, v138, v142
	v_cvt_pk_bf16_f32 v154, v131, v135
	v_cvt_pk_bf16_f32 v155, v139, v143
	ds_write_b64 v4, v[172:173] offset:8
	ds_write_b64 v4, v[174:175] offset:280
	ds_write_b64 v4, v[146:147] offset:552
	ds_write_b64 v4, v[154:155] offset:824
	v_lshlrev_b32_e32 v128, 16, v48
	v_and_b32_e32 v129, 0xffff0000, v48
	v_lshlrev_b32_e32 v130, 16, v49
	v_and_b32_e32 v131, 0xffff0000, v49
	v_lshlrev_b32_e32 v132, 16, v50
	v_and_b32_e32 v133, 0xffff0000, v50
	v_lshlrev_b32_e32 v134, 16, v51
	v_and_b32_e32 v135, 0xffff0000, v51
	v_lshlrev_b32_e32 v136, 16, v52
	v_and_b32_e32 v137, 0xffff0000, v52
	v_lshlrev_b32_e32 v138, 16, v53
	v_and_b32_e32 v139, 0xffff0000, v53
	v_lshlrev_b32_e32 v140, 16, v54
	v_and_b32_e32 v141, 0xffff0000, v54
	v_lshlrev_b32_e32 v142, 16, v55
	v_and_b32_e32 v143, 0xffff0000, v55
	v_add_f32_e32 v156, v128, v129
	v_add_f32_e32 v160, v130, v131
	v_add_f32_e32 v157, v132, v133
	v_add_f32_e32 v161, v134, v135
	v_add_f32_e32 v158, v136, v137
	v_add_f32_e32 v162, v138, v139
	v_add_f32_e32 v159, v140, v141
	v_add_f32_e32 v163, v142, v143
	v_add_f32_e32 v156, v156, v160
	v_add_f32_e32 v157, v157, v161
	v_add_f32_e32 v158, v158, v162
	v_add_f32_e32 v159, v159, v163
	v_add_f32_dpp v156, v156, v156 quad_perm:[1,0,3,2] row_mask:0xf bank_mask:0xf
	v_add_f32_dpp v157, v157, v157 quad_perm:[1,0,3,2] row_mask:0xf bank_mask:0xf
	v_add_f32_dpp v158, v158, v158 quad_perm:[1,0,3,2] row_mask:0xf bank_mask:0xf
	v_add_f32_dpp v159, v159, v159 quad_perm:[1,0,3,2] row_mask:0xf bank_mask:0xf
	v_add_f32_dpp v156, v156, v156 quad_perm:[2,3,0,1] row_mask:0xf bank_mask:0xf
	v_add_f32_dpp v157, v157, v157 quad_perm:[2,3,0,1] row_mask:0xf bank_mask:0xf
	v_add_f32_dpp v158, v158, v158 quad_perm:[2,3,0,1] row_mask:0xf bank_mask:0xf
	v_add_f32_dpp v159, v159, v159 quad_perm:[2,3,0,1] row_mask:0xf bank_mask:0xf
	v_add_f32_dpp v156, v156, v156 row_half_mirror row_mask:0xf bank_mask:0xf
	v_add_f32_dpp v157, v157, v157 row_half_mirror row_mask:0xf bank_mask:0xf
	v_add_f32_dpp v158, v158, v158 row_half_mirror row_mask:0xf bank_mask:0xf
	v_add_f32_dpp v159, v159, v159 row_half_mirror row_mask:0xf bank_mask:0xf
	v_add_f32_dpp v156, v156, v156 row_mirror row_mask:0xf bank_mask:0xf
	v_add_f32_dpp v157, v157, v157 row_mirror row_mask:0xf bank_mask:0xf
	v_add_f32_dpp v158, v158, v158 row_mirror row_mask:0xf bank_mask:0xf
	v_add_f32_dpp v159, v159, v159 row_mirror row_mask:0xf bank_mask:0xf
	v_mov_b32_e32 v160, v156
	v_mov_b32_e32 v161, v157
	v_mov_b32_e32 v162, v158
	v_mov_b32_e32 v163, v159
	v_permlane16_swap_b32_e32 v156, v160
	v_permlane16_swap_b32_e32 v157, v161
	v_permlane16_swap_b32_e32 v158, v162
	v_permlane16_swap_b32_e32 v159, v163
	v_add_f32_e32 v156, v156, v160
	v_add_f32_e32 v157, v157, v161
	v_add_f32_e32 v158, v158, v162
	v_add_f32_e32 v159, v159, v163
	v_mov_b32_e32 v160, v156
	v_mov_b32_e32 v161, v157
	v_mov_b32_e32 v162, v158
	v_mov_b32_e32 v163, v159
	v_permlane32_swap_b32_e32 v156, v160
	v_permlane32_swap_b32_e32 v157, v161
	v_permlane32_swap_b32_e32 v158, v162
	v_permlane32_swap_b32_e32 v159, v163
	v_add_f32_e32 v156, v156, v160
	v_add_f32_e32 v157, v157, v161
	v_add_f32_e32 v158, v158, v162
	v_add_f32_e32 v159, v159, v163
	v_fmac_f32_e32 v129, 0xbb800000, v156
	v_fmac_f32_e32 v131, 0xbb800000, v156
	v_fmac_f32_e32 v130, 0xbb800000, v156
	v_fmac_f32_e32 v128, 0xbb800000, v156
	v_fmac_f32_e32 v133, 0xbb800000, v157
	v_fmac_f32_e32 v135, 0xbb800000, v157
	v_fmac_f32_e32 v134, 0xbb800000, v157
	v_fmac_f32_e32 v132, 0xbb800000, v157
	v_fmac_f32_e32 v137, 0xbb800000, v158
	v_fmac_f32_e32 v139, 0xbb800000, v158
	v_fmac_f32_e32 v138, 0xbb800000, v158
	v_fmac_f32_e32 v136, 0xbb800000, v158
	v_fmac_f32_e32 v141, 0xbb800000, v159
	v_fmac_f32_e32 v143, 0xbb800000, v159
	v_fmac_f32_e32 v142, 0xbb800000, v159
	v_fmac_f32_e32 v140, 0xbb800000, v159
	v_mul_f32_e32 v156, v128, v128
	v_mul_f32_e32 v160, v129, v129
	v_mul_f32_e32 v164, v130, v130
	v_mul_f32_e32 v168, v131, v131
	v_mul_f32_e32 v157, v132, v132
	v_mul_f32_e32 v161, v133, v133
	v_mul_f32_e32 v165, v134, v134
	v_mul_f32_e32 v169, v135, v135
	v_mul_f32_e32 v158, v136, v136
	v_mul_f32_e32 v162, v137, v137
	v_mul_f32_e32 v166, v138, v138
	v_mul_f32_e32 v170, v139, v139
	v_mul_f32_e32 v159, v140, v140
	v_mul_f32_e32 v163, v141, v141
	v_mul_f32_e32 v167, v142, v142
	v_mul_f32_e32 v171, v143, v143
	v_add_f32_e32 v156, v160, v156
	v_add_f32_e32 v164, v164, v168
	v_add_f32_e32 v157, v161, v157
	v_add_f32_e32 v165, v165, v169
	v_add_f32_e32 v158, v162, v158
	v_add_f32_e32 v166, v166, v170
	v_add_f32_e32 v159, v163, v159
	v_add_f32_e32 v167, v167, v171
	v_add_f32_e32 v156, v156, v164
	v_add_f32_e32 v157, v157, v165
	v_add_f32_e32 v158, v158, v166
	v_add_f32_e32 v159, v159, v167
	v_add_f32_dpp v156, v156, v156 quad_perm:[1,0,3,2] row_mask:0xf bank_mask:0xf
	v_add_f32_dpp v157, v157, v157 quad_perm:[1,0,3,2] row_mask:0xf bank_mask:0xf
	v_add_f32_dpp v158, v158, v158 quad_perm:[1,0,3,2] row_mask:0xf bank_mask:0xf
	v_add_f32_dpp v159, v159, v159 quad_perm:[1,0,3,2] row_mask:0xf bank_mask:0xf
	v_add_f32_dpp v156, v156, v156 quad_perm:[2,3,0,1] row_mask:0xf bank_mask:0xf
	v_add_f32_dpp v157, v157, v157 quad_perm:[2,3,0,1] row_mask:0xf bank_mask:0xf
	v_add_f32_dpp v158, v158, v158 quad_perm:[2,3,0,1] row_mask:0xf bank_mask:0xf
	v_add_f32_dpp v159, v159, v159 quad_perm:[2,3,0,1] row_mask:0xf bank_mask:0xf
	v_add_f32_dpp v156, v156, v156 row_half_mirror row_mask:0xf bank_mask:0xf
	v_add_f32_dpp v157, v157, v157 row_half_mirror row_mask:0xf bank_mask:0xf
	v_add_f32_dpp v158, v158, v158 row_half_mirror row_mask:0xf bank_mask:0xf
	v_add_f32_dpp v159, v159, v159 row_half_mirror row_mask:0xf bank_mask:0xf
	v_add_f32_dpp v156, v156, v156 row_mirror row_mask:0xf bank_mask:0xf
	v_add_f32_dpp v157, v157, v157 row_mirror row_mask:0xf bank_mask:0xf
	v_add_f32_dpp v158, v158, v158 row_mirror row_mask:0xf bank_mask:0xf
	v_add_f32_dpp v159, v159, v159 row_mirror row_mask:0xf bank_mask:0xf
	v_mov_b32_e32 v160, v156
	v_mov_b32_e32 v161, v157
	v_mov_b32_e32 v162, v158
	v_mov_b32_e32 v163, v159
	v_permlane16_swap_b32_e32 v156, v160
	v_permlane16_swap_b32_e32 v157, v161
	v_permlane16_swap_b32_e32 v158, v162
	v_permlane16_swap_b32_e32 v159, v163
	v_add_f32_e32 v156, v156, v160
	v_add_f32_e32 v157, v157, v161
	v_add_f32_e32 v158, v158, v162
	v_add_f32_e32 v159, v159, v163
	v_mov_b32_e32 v160, v156
	v_mov_b32_e32 v161, v157
	v_mov_b32_e32 v162, v158
	v_mov_b32_e32 v163, v159
	v_permlane32_swap_b32_e32 v156, v160
	v_permlane32_swap_b32_e32 v157, v161
	v_permlane32_swap_b32_e32 v158, v162
	v_permlane32_swap_b32_e32 v159, v163
	v_add_f32_e32 v156, v156, v160
	v_add_f32_e32 v157, v157, v161
	v_add_f32_e32 v158, v158, v162
	v_add_f32_e32 v159, v159, v163
	v_fmamk_f32 v156, v156, 0x3b800000, v194
	v_fmamk_f32 v157, v157, 0x3b800000, v194
	v_fmamk_f32 v158, v158, 0x3b800000, v194
	v_fmamk_f32 v159, v159, 0x3b800000, v194
	v_cmp_gt_f32_e32 vcc, s13, v156
	v_mul_f32_e32 v164, 0x4f800000, v156
	s_nop 0
	v_cndmask_b32_e32 v156, v156, v164, vcc
	v_sqrt_f32_e32 v164, v156
	s_nop 0
	v_add_u32_e32 v165, -1, v164
	v_fma_f32 v166, -v165, v164, v156
	v_cmp_ge_f32_e64 s[36:37], 0, v166
	v_add_u32_e32 v166, 1, v164
	s_nop 0
	v_cndmask_b32_e64 v165, v164, v165, s[36:37]
	v_fma_f32 v164, -v166, v164, v156
	v_cmp_lt_f32_e64 s[36:37], 0, v164
	s_nop 1
	v_cndmask_b32_e64 v164, v165, v166, s[36:37]
	v_mul_f32_e32 v165, 0x37800000, v164
	v_cndmask_b32_e32 v164, v164, v165, vcc
	v_cmp_class_f32_e32 vcc, v156, v196
	s_nop 1
	v_cndmask_b32_e32 v156, v164, v156, vcc
	v_div_scale_f32 v164, s[36:37], v156, v156, 1.0
	v_rcp_f32_e32 v165, v164
	s_nop 0
	v_fma_f32 v166, -v164, v165, 1.0
	v_fmac_f32_e32 v165, v166, v165
	v_div_scale_f32 v166, vcc, 1.0, v156, 1.0
	v_mul_f32_e32 v167, v166, v165
	v_fma_f32 v168, -v164, v167, v166
	v_fmac_f32_e32 v167, v168, v165
	v_fma_f32 v164, -v164, v167, v166
	v_div_fmas_f32 v164, v164, v165, v167
	v_div_fixup_f32 v156, v164, v156, 1.0
	v_cmp_gt_f32_e32 vcc, s13, v157
	v_mul_f32_e32 v164, 0x4f800000, v157
	s_nop 0
	v_cndmask_b32_e32 v157, v157, v164, vcc
	v_sqrt_f32_e32 v164, v157
	s_nop 0
	v_add_u32_e32 v165, -1, v164
	v_fma_f32 v166, -v165, v164, v157
	v_cmp_ge_f32_e64 s[36:37], 0, v166
	v_add_u32_e32 v166, 1, v164
	s_nop 0
	v_cndmask_b32_e64 v165, v164, v165, s[36:37]
	v_fma_f32 v164, -v166, v164, v157
	v_cmp_lt_f32_e64 s[36:37], 0, v164
	s_nop 1
	v_cndmask_b32_e64 v164, v165, v166, s[36:37]
	v_mul_f32_e32 v165, 0x37800000, v164
	v_cndmask_b32_e32 v164, v164, v165, vcc
	v_cmp_class_f32_e32 vcc, v157, v196
	s_nop 1
	v_cndmask_b32_e32 v157, v164, v157, vcc
	v_div_scale_f32 v164, s[36:37], v157, v157, 1.0
	v_rcp_f32_e32 v165, v164
	s_nop 0
	v_fma_f32 v166, -v164, v165, 1.0
	v_fmac_f32_e32 v165, v166, v165
	v_div_scale_f32 v166, vcc, 1.0, v157, 1.0
	v_mul_f32_e32 v167, v166, v165
	v_fma_f32 v168, -v164, v167, v166
	v_fmac_f32_e32 v167, v168, v165
	v_fma_f32 v164, -v164, v167, v166
	v_div_fmas_f32 v164, v164, v165, v167
	v_div_fixup_f32 v157, v164, v157, 1.0
	v_cmp_gt_f32_e32 vcc, s13, v158
	v_mul_f32_e32 v164, 0x4f800000, v158
	s_nop 0
	v_cndmask_b32_e32 v158, v158, v164, vcc
	v_sqrt_f32_e32 v164, v158
	s_nop 0
	v_add_u32_e32 v165, -1, v164
	v_fma_f32 v166, -v165, v164, v158
	v_cmp_ge_f32_e64 s[36:37], 0, v166
	v_add_u32_e32 v166, 1, v164
	s_nop 0
	v_cndmask_b32_e64 v165, v164, v165, s[36:37]
	v_fma_f32 v164, -v166, v164, v158
	v_cmp_lt_f32_e64 s[36:37], 0, v164
	s_nop 1
	v_cndmask_b32_e64 v164, v165, v166, s[36:37]
	v_mul_f32_e32 v165, 0x37800000, v164
	v_cndmask_b32_e32 v164, v164, v165, vcc
	v_cmp_class_f32_e32 vcc, v158, v196
	s_nop 1
	v_cndmask_b32_e32 v158, v164, v158, vcc
	v_div_scale_f32 v164, s[36:37], v158, v158, 1.0
	v_rcp_f32_e32 v165, v164
	s_nop 0
	v_fma_f32 v166, -v164, v165, 1.0
	v_fmac_f32_e32 v165, v166, v165
	v_div_scale_f32 v166, vcc, 1.0, v158, 1.0
	v_mul_f32_e32 v167, v166, v165
	v_fma_f32 v168, -v164, v167, v166
	v_fmac_f32_e32 v167, v168, v165
	v_fma_f32 v164, -v164, v167, v166
	v_div_fmas_f32 v164, v164, v165, v167
	v_div_fixup_f32 v158, v164, v158, 1.0
	v_cmp_gt_f32_e32 vcc, s13, v159
	v_mul_f32_e32 v164, 0x4f800000, v159
	s_nop 0
	v_cndmask_b32_e32 v159, v159, v164, vcc
	v_sqrt_f32_e32 v164, v159
	s_nop 0
	v_add_u32_e32 v165, -1, v164
	v_fma_f32 v166, -v165, v164, v159
	v_cmp_ge_f32_e64 s[36:37], 0, v166
	v_add_u32_e32 v166, 1, v164
	s_nop 0
	v_cndmask_b32_e64 v165, v164, v165, s[36:37]
	v_fma_f32 v164, -v166, v164, v159
	v_cmp_lt_f32_e64 s[36:37], 0, v164
	s_nop 1
	v_cndmask_b32_e64 v164, v165, v166, s[36:37]
	v_mul_f32_e32 v165, 0x37800000, v164
	v_cndmask_b32_e32 v164, v164, v165, vcc
	v_cmp_class_f32_e32 vcc, v159, v196
	s_nop 1
	v_cndmask_b32_e32 v159, v164, v159, vcc
	v_div_scale_f32 v164, s[36:37], v159, v159, 1.0
	v_rcp_f32_e32 v165, v164
	s_nop 0
	v_fma_f32 v166, -v164, v165, 1.0
	v_fmac_f32_e32 v165, v166, v165
	v_div_scale_f32 v166, vcc, 1.0, v159, 1.0
	v_mul_f32_e32 v167, v166, v165
	v_fma_f32 v168, -v164, v167, v166
	v_fmac_f32_e32 v167, v168, v165
	v_fma_f32 v164, -v164, v167, v166
	v_div_fmas_f32 v164, v164, v165, v167
	v_div_fixup_f32 v159, v164, v159, 1.0
	v_mul_f32_e32 v128, v128, v156
	v_mul_f32_e32 v129, v129, v156
	v_mul_f32_e32 v130, v130, v156
	v_mul_f32_e32 v131, v131, v156
	v_mul_f32_e32 v132, v132, v157
	v_mul_f32_e32 v133, v133, v157
	v_mul_f32_e32 v134, v134, v157
	v_mul_f32_e32 v135, v135, v157
	v_mul_f32_e32 v136, v136, v158
	v_mul_f32_e32 v137, v137, v158
	v_mul_f32_e32 v138, v138, v158
	v_mul_f32_e32 v139, v139, v158
	v_mul_f32_e32 v140, v140, v159
	v_mul_f32_e32 v141, v141, v159
	v_mul_f32_e32 v142, v142, v159
	v_mul_f32_e32 v143, v143, v159
	v_mul_f32_e32 v128, v10, v128
	v_mul_f32_e32 v129, v11, v129
	v_mul_f32_e32 v130, v12, v130
	v_mul_f32_e32 v131, v13, v131
	v_mul_f32_e32 v132, v10, v132
	v_mul_f32_e32 v133, v11, v133
	v_mul_f32_e32 v134, v12, v134
	v_mul_f32_e32 v135, v13, v135
	v_mul_f32_e32 v136, v10, v136
	v_mul_f32_e32 v137, v11, v137
	v_mul_f32_e32 v138, v12, v138
	v_mul_f32_e32 v139, v13, v139
	v_mul_f32_e32 v140, v10, v140
	v_mul_f32_e32 v141, v11, v141
	v_mul_f32_e32 v142, v12, v142
	v_mul_f32_e32 v143, v13, v143
	v_cvt_pk_bf16_f32 v172, v128, v132
	v_cvt_pk_bf16_f32 v173, v136, v140
	v_cvt_pk_bf16_f32 v174, v129, v133
	v_cvt_pk_bf16_f32 v175, v137, v141
	v_cvt_pk_bf16_f32 v146, v130, v134
	v_cvt_pk_bf16_f32 v147, v138, v142
	v_cvt_pk_bf16_f32 v154, v131, v135
	v_cvt_pk_bf16_f32 v155, v139, v143
	ds_write_b64 v4, v[172:173] offset:16
	ds_write_b64 v4, v[174:175] offset:288
	ds_write_b64 v4, v[146:147] offset:560
	ds_write_b64 v4, v[154:155] offset:832
	v_lshlrev_b32_e32 v128, 16, v56
	v_and_b32_e32 v129, 0xffff0000, v56
	v_lshlrev_b32_e32 v130, 16, v57
	v_and_b32_e32 v131, 0xffff0000, v57
	v_lshlrev_b32_e32 v132, 16, v58
	v_and_b32_e32 v133, 0xffff0000, v58
	v_lshlrev_b32_e32 v134, 16, v59
	v_and_b32_e32 v135, 0xffff0000, v59
	v_lshlrev_b32_e32 v136, 16, v60
	v_and_b32_e32 v137, 0xffff0000, v60
	v_lshlrev_b32_e32 v138, 16, v61
	v_and_b32_e32 v139, 0xffff0000, v61
	v_lshlrev_b32_e32 v140, 16, v62
	v_and_b32_e32 v141, 0xffff0000, v62
	v_lshlrev_b32_e32 v142, 16, v63
	v_and_b32_e32 v143, 0xffff0000, v63
	v_add_f32_e32 v156, v128, v129
	v_add_f32_e32 v160, v130, v131
	v_add_f32_e32 v157, v132, v133
	v_add_f32_e32 v161, v134, v135
	v_add_f32_e32 v158, v136, v137
	v_add_f32_e32 v162, v138, v139
	v_add_f32_e32 v159, v140, v141
	v_add_f32_e32 v163, v142, v143
	v_add_f32_e32 v156, v156, v160
	v_add_f32_e32 v157, v157, v161
	v_add_f32_e32 v158, v158, v162
	v_add_f32_e32 v159, v159, v163
	v_add_f32_dpp v156, v156, v156 quad_perm:[1,0,3,2] row_mask:0xf bank_mask:0xf
	v_add_f32_dpp v157, v157, v157 quad_perm:[1,0,3,2] row_mask:0xf bank_mask:0xf
	v_add_f32_dpp v158, v158, v158 quad_perm:[1,0,3,2] row_mask:0xf bank_mask:0xf
	v_add_f32_dpp v159, v159, v159 quad_perm:[1,0,3,2] row_mask:0xf bank_mask:0xf
	v_add_f32_dpp v156, v156, v156 quad_perm:[2,3,0,1] row_mask:0xf bank_mask:0xf
	v_add_f32_dpp v157, v157, v157 quad_perm:[2,3,0,1] row_mask:0xf bank_mask:0xf
	v_add_f32_dpp v158, v158, v158 quad_perm:[2,3,0,1] row_mask:0xf bank_mask:0xf
	v_add_f32_dpp v159, v159, v159 quad_perm:[2,3,0,1] row_mask:0xf bank_mask:0xf
	v_add_f32_dpp v156, v156, v156 row_half_mirror row_mask:0xf bank_mask:0xf
	v_add_f32_dpp v157, v157, v157 row_half_mirror row_mask:0xf bank_mask:0xf
	v_add_f32_dpp v158, v158, v158 row_half_mirror row_mask:0xf bank_mask:0xf
	v_add_f32_dpp v159, v159, v159 row_half_mirror row_mask:0xf bank_mask:0xf
	v_add_f32_dpp v156, v156, v156 row_mirror row_mask:0xf bank_mask:0xf
	v_add_f32_dpp v157, v157, v157 row_mirror row_mask:0xf bank_mask:0xf
	v_add_f32_dpp v158, v158, v158 row_mirror row_mask:0xf bank_mask:0xf
	v_add_f32_dpp v159, v159, v159 row_mirror row_mask:0xf bank_mask:0xf
	v_mov_b32_e32 v160, v156
	v_mov_b32_e32 v161, v157
	v_mov_b32_e32 v162, v158
	v_mov_b32_e32 v163, v159
	v_permlane16_swap_b32_e32 v156, v160
	v_permlane16_swap_b32_e32 v157, v161
	v_permlane16_swap_b32_e32 v158, v162
	v_permlane16_swap_b32_e32 v159, v163
	v_add_f32_e32 v156, v156, v160
	v_add_f32_e32 v157, v157, v161
	v_add_f32_e32 v158, v158, v162
	v_add_f32_e32 v159, v159, v163
	v_mov_b32_e32 v160, v156
	v_mov_b32_e32 v161, v157
	v_mov_b32_e32 v162, v158
	v_mov_b32_e32 v163, v159
	v_permlane32_swap_b32_e32 v156, v160
	v_permlane32_swap_b32_e32 v157, v161
	v_permlane32_swap_b32_e32 v158, v162
	v_permlane32_swap_b32_e32 v159, v163
	v_add_f32_e32 v156, v156, v160
	v_add_f32_e32 v157, v157, v161
	v_add_f32_e32 v158, v158, v162
	v_add_f32_e32 v159, v159, v163
	v_fmac_f32_e32 v129, 0xbb800000, v156
	v_fmac_f32_e32 v131, 0xbb800000, v156
	v_fmac_f32_e32 v130, 0xbb800000, v156
	v_fmac_f32_e32 v128, 0xbb800000, v156
	v_fmac_f32_e32 v133, 0xbb800000, v157
	v_fmac_f32_e32 v135, 0xbb800000, v157
	v_fmac_f32_e32 v134, 0xbb800000, v157
	v_fmac_f32_e32 v132, 0xbb800000, v157
	v_fmac_f32_e32 v137, 0xbb800000, v158
	v_fmac_f32_e32 v139, 0xbb800000, v158
	v_fmac_f32_e32 v138, 0xbb800000, v158
	v_fmac_f32_e32 v136, 0xbb800000, v158
	v_fmac_f32_e32 v141, 0xbb800000, v159
	v_fmac_f32_e32 v143, 0xbb800000, v159
	v_fmac_f32_e32 v142, 0xbb800000, v159
	v_fmac_f32_e32 v140, 0xbb800000, v159
	v_mul_f32_e32 v156, v128, v128
	v_mul_f32_e32 v160, v129, v129
	v_mul_f32_e32 v164, v130, v130
	v_mul_f32_e32 v168, v131, v131
	v_mul_f32_e32 v157, v132, v132
	v_mul_f32_e32 v161, v133, v133
	v_mul_f32_e32 v165, v134, v134
	v_mul_f32_e32 v169, v135, v135
	v_mul_f32_e32 v158, v136, v136
	v_mul_f32_e32 v162, v137, v137
	v_mul_f32_e32 v166, v138, v138
	v_mul_f32_e32 v170, v139, v139
	v_mul_f32_e32 v159, v140, v140
	v_mul_f32_e32 v163, v141, v141
	v_mul_f32_e32 v167, v142, v142
	v_mul_f32_e32 v171, v143, v143
	v_add_f32_e32 v156, v160, v156
	v_add_f32_e32 v164, v164, v168
	v_add_f32_e32 v157, v161, v157
	v_add_f32_e32 v165, v165, v169
	v_add_f32_e32 v158, v162, v158
	v_add_f32_e32 v166, v166, v170
	v_add_f32_e32 v159, v163, v159
	v_add_f32_e32 v167, v167, v171
	v_add_f32_e32 v156, v156, v164
	v_add_f32_e32 v157, v157, v165
	v_add_f32_e32 v158, v158, v166
	v_add_f32_e32 v159, v159, v167
	v_add_f32_dpp v156, v156, v156 quad_perm:[1,0,3,2] row_mask:0xf bank_mask:0xf
	v_add_f32_dpp v157, v157, v157 quad_perm:[1,0,3,2] row_mask:0xf bank_mask:0xf
	v_add_f32_dpp v158, v158, v158 quad_perm:[1,0,3,2] row_mask:0xf bank_mask:0xf
	v_add_f32_dpp v159, v159, v159 quad_perm:[1,0,3,2] row_mask:0xf bank_mask:0xf
	v_add_f32_dpp v156, v156, v156 quad_perm:[2,3,0,1] row_mask:0xf bank_mask:0xf
	v_add_f32_dpp v157, v157, v157 quad_perm:[2,3,0,1] row_mask:0xf bank_mask:0xf
	v_add_f32_dpp v158, v158, v158 quad_perm:[2,3,0,1] row_mask:0xf bank_mask:0xf
	v_add_f32_dpp v159, v159, v159 quad_perm:[2,3,0,1] row_mask:0xf bank_mask:0xf
	v_add_f32_dpp v156, v156, v156 row_half_mirror row_mask:0xf bank_mask:0xf
	v_add_f32_dpp v157, v157, v157 row_half_mirror row_mask:0xf bank_mask:0xf
	v_add_f32_dpp v158, v158, v158 row_half_mirror row_mask:0xf bank_mask:0xf
	v_add_f32_dpp v159, v159, v159 row_half_mirror row_mask:0xf bank_mask:0xf
	v_add_f32_dpp v156, v156, v156 row_mirror row_mask:0xf bank_mask:0xf
	v_add_f32_dpp v157, v157, v157 row_mirror row_mask:0xf bank_mask:0xf
	v_add_f32_dpp v158, v158, v158 row_mirror row_mask:0xf bank_mask:0xf
	v_add_f32_dpp v159, v159, v159 row_mirror row_mask:0xf bank_mask:0xf
	v_mov_b32_e32 v160, v156
	v_mov_b32_e32 v161, v157
	v_mov_b32_e32 v162, v158
	v_mov_b32_e32 v163, v159
	v_permlane16_swap_b32_e32 v156, v160
	v_permlane16_swap_b32_e32 v157, v161
	v_permlane16_swap_b32_e32 v158, v162
	v_permlane16_swap_b32_e32 v159, v163
	v_add_f32_e32 v156, v156, v160
	v_add_f32_e32 v157, v157, v161
	v_add_f32_e32 v158, v158, v162
	v_add_f32_e32 v159, v159, v163
	v_mov_b32_e32 v160, v156
	v_mov_b32_e32 v161, v157
	v_mov_b32_e32 v162, v158
	v_mov_b32_e32 v163, v159
	v_permlane32_swap_b32_e32 v156, v160
	v_permlane32_swap_b32_e32 v157, v161
	v_permlane32_swap_b32_e32 v158, v162
	v_permlane32_swap_b32_e32 v159, v163
	v_add_f32_e32 v156, v156, v160
	v_add_f32_e32 v157, v157, v161
	v_add_f32_e32 v158, v158, v162
	v_add_f32_e32 v159, v159, v163
	v_fmamk_f32 v156, v156, 0x3b800000, v194
	v_fmamk_f32 v157, v157, 0x3b800000, v194
	v_fmamk_f32 v158, v158, 0x3b800000, v194
	v_fmamk_f32 v159, v159, 0x3b800000, v194
	v_cmp_gt_f32_e32 vcc, s13, v156
	v_mul_f32_e32 v164, 0x4f800000, v156
	s_nop 0
	v_cndmask_b32_e32 v156, v156, v164, vcc
	v_sqrt_f32_e32 v164, v156
	s_nop 0
	v_add_u32_e32 v165, -1, v164
	v_fma_f32 v166, -v165, v164, v156
	v_cmp_ge_f32_e64 s[36:37], 0, v166
	v_add_u32_e32 v166, 1, v164
	s_nop 0
	v_cndmask_b32_e64 v165, v164, v165, s[36:37]
	v_fma_f32 v164, -v166, v164, v156
	v_cmp_lt_f32_e64 s[36:37], 0, v164
	s_nop 1
	v_cndmask_b32_e64 v164, v165, v166, s[36:37]
	v_mul_f32_e32 v165, 0x37800000, v164
	v_cndmask_b32_e32 v164, v164, v165, vcc
	v_cmp_class_f32_e32 vcc, v156, v196
	s_nop 1
	v_cndmask_b32_e32 v156, v164, v156, vcc
	v_div_scale_f32 v164, s[36:37], v156, v156, 1.0
	v_rcp_f32_e32 v165, v164
	s_nop 0
	v_fma_f32 v166, -v164, v165, 1.0
	v_fmac_f32_e32 v165, v166, v165
	v_div_scale_f32 v166, vcc, 1.0, v156, 1.0
	v_mul_f32_e32 v167, v166, v165
	v_fma_f32 v168, -v164, v167, v166
	v_fmac_f32_e32 v167, v168, v165
	v_fma_f32 v164, -v164, v167, v166
	v_div_fmas_f32 v164, v164, v165, v167
	v_div_fixup_f32 v156, v164, v156, 1.0
	v_cmp_gt_f32_e32 vcc, s13, v157
	v_mul_f32_e32 v164, 0x4f800000, v157
	s_nop 0
	v_cndmask_b32_e32 v157, v157, v164, vcc
	v_sqrt_f32_e32 v164, v157
	s_nop 0
	v_add_u32_e32 v165, -1, v164
	v_fma_f32 v166, -v165, v164, v157
	v_cmp_ge_f32_e64 s[36:37], 0, v166
	v_add_u32_e32 v166, 1, v164
	s_nop 0
	v_cndmask_b32_e64 v165, v164, v165, s[36:37]
	v_fma_f32 v164, -v166, v164, v157
	v_cmp_lt_f32_e64 s[36:37], 0, v164
	s_nop 1
	v_cndmask_b32_e64 v164, v165, v166, s[36:37]
	v_mul_f32_e32 v165, 0x37800000, v164
	v_cndmask_b32_e32 v164, v164, v165, vcc
	v_cmp_class_f32_e32 vcc, v157, v196
	s_nop 1
	v_cndmask_b32_e32 v157, v164, v157, vcc
	v_div_scale_f32 v164, s[36:37], v157, v157, 1.0
	v_rcp_f32_e32 v165, v164
	s_nop 0
	v_fma_f32 v166, -v164, v165, 1.0
	v_fmac_f32_e32 v165, v166, v165
	v_div_scale_f32 v166, vcc, 1.0, v157, 1.0
	v_mul_f32_e32 v167, v166, v165
	v_fma_f32 v168, -v164, v167, v166
	v_fmac_f32_e32 v167, v168, v165
	v_fma_f32 v164, -v164, v167, v166
	v_div_fmas_f32 v164, v164, v165, v167
	v_div_fixup_f32 v157, v164, v157, 1.0
	v_cmp_gt_f32_e32 vcc, s13, v158
	v_mul_f32_e32 v164, 0x4f800000, v158
	s_nop 0
	v_cndmask_b32_e32 v158, v158, v164, vcc
	v_sqrt_f32_e32 v164, v158
	s_nop 0
	v_add_u32_e32 v165, -1, v164
	v_fma_f32 v166, -v165, v164, v158
	v_cmp_ge_f32_e64 s[36:37], 0, v166
	v_add_u32_e32 v166, 1, v164
	s_nop 0
	v_cndmask_b32_e64 v165, v164, v165, s[36:37]
	v_fma_f32 v164, -v166, v164, v158
	v_cmp_lt_f32_e64 s[36:37], 0, v164
	s_nop 1
	v_cndmask_b32_e64 v164, v165, v166, s[36:37]
	v_mul_f32_e32 v165, 0x37800000, v164
	v_cndmask_b32_e32 v164, v164, v165, vcc
	v_cmp_class_f32_e32 vcc, v158, v196
	s_nop 1
	v_cndmask_b32_e32 v158, v164, v158, vcc
	v_div_scale_f32 v164, s[36:37], v158, v158, 1.0
	v_rcp_f32_e32 v165, v164
	s_nop 0
	v_fma_f32 v166, -v164, v165, 1.0
	v_fmac_f32_e32 v165, v166, v165
	v_div_scale_f32 v166, vcc, 1.0, v158, 1.0
	v_mul_f32_e32 v167, v166, v165
	v_fma_f32 v168, -v164, v167, v166
	v_fmac_f32_e32 v167, v168, v165
	v_fma_f32 v164, -v164, v167, v166
	v_div_fmas_f32 v164, v164, v165, v167
	v_div_fixup_f32 v158, v164, v158, 1.0
	v_cmp_gt_f32_e32 vcc, s13, v159
	v_mul_f32_e32 v164, 0x4f800000, v159
	s_nop 0
	v_cndmask_b32_e32 v159, v159, v164, vcc
	v_sqrt_f32_e32 v164, v159
	s_nop 0
	v_add_u32_e32 v165, -1, v164
	v_fma_f32 v166, -v165, v164, v159
	v_cmp_ge_f32_e64 s[36:37], 0, v166
	v_add_u32_e32 v166, 1, v164
	s_nop 0
	v_cndmask_b32_e64 v165, v164, v165, s[36:37]
	v_fma_f32 v164, -v166, v164, v159
	v_cmp_lt_f32_e64 s[36:37], 0, v164
	s_nop 1
	v_cndmask_b32_e64 v164, v165, v166, s[36:37]
	v_mul_f32_e32 v165, 0x37800000, v164
	v_cndmask_b32_e32 v164, v164, v165, vcc
	v_cmp_class_f32_e32 vcc, v159, v196
	s_nop 1
	v_cndmask_b32_e32 v159, v164, v159, vcc
	v_div_scale_f32 v164, s[36:37], v159, v159, 1.0
	v_rcp_f32_e32 v165, v164
	s_nop 0
	v_fma_f32 v166, -v164, v165, 1.0
	v_fmac_f32_e32 v165, v166, v165
	v_div_scale_f32 v166, vcc, 1.0, v159, 1.0
	v_mul_f32_e32 v167, v166, v165
	v_fma_f32 v168, -v164, v167, v166
	v_fmac_f32_e32 v167, v168, v165
	v_fma_f32 v164, -v164, v167, v166
	v_div_fmas_f32 v164, v164, v165, v167
	v_div_fixup_f32 v159, v164, v159, 1.0
	v_mul_f32_e32 v128, v128, v156
	v_mul_f32_e32 v129, v129, v156
	v_mul_f32_e32 v130, v130, v156
	v_mul_f32_e32 v131, v131, v156
	v_mul_f32_e32 v132, v132, v157
	v_mul_f32_e32 v133, v133, v157
	v_mul_f32_e32 v134, v134, v157
	v_mul_f32_e32 v135, v135, v157
	v_mul_f32_e32 v136, v136, v158
	v_mul_f32_e32 v137, v137, v158
	v_mul_f32_e32 v138, v138, v158
	v_mul_f32_e32 v139, v139, v158
	v_mul_f32_e32 v140, v140, v159
	v_mul_f32_e32 v141, v141, v159
	v_mul_f32_e32 v142, v142, v159
	v_mul_f32_e32 v143, v143, v159
	v_mul_f32_e32 v128, v10, v128
	v_mul_f32_e32 v129, v11, v129
	v_mul_f32_e32 v130, v12, v130
	v_mul_f32_e32 v131, v13, v131
	v_mul_f32_e32 v132, v10, v132
	v_mul_f32_e32 v133, v11, v133
	v_mul_f32_e32 v134, v12, v134
	v_mul_f32_e32 v135, v13, v135
	v_mul_f32_e32 v136, v10, v136
	v_mul_f32_e32 v137, v11, v137
	v_mul_f32_e32 v138, v12, v138
	v_mul_f32_e32 v139, v13, v139
	v_mul_f32_e32 v140, v10, v140
	v_mul_f32_e32 v141, v11, v141
	v_mul_f32_e32 v142, v12, v142
	v_mul_f32_e32 v143, v13, v143
	v_cvt_pk_bf16_f32 v172, v128, v132
	v_cvt_pk_bf16_f32 v173, v136, v140
	v_cvt_pk_bf16_f32 v174, v129, v133
	v_cvt_pk_bf16_f32 v175, v137, v141
	v_cvt_pk_bf16_f32 v146, v130, v134
	v_cvt_pk_bf16_f32 v147, v138, v142
	v_cvt_pk_bf16_f32 v154, v131, v135
	v_cvt_pk_bf16_f32 v155, v139, v143
	ds_write_b64 v4, v[172:173] offset:24
	ds_write_b64 v4, v[174:175] offset:296
	ds_write_b64 v4, v[146:147] offset:568
	ds_write_b64 v4, v[154:155] offset:840
	s_waitcnt vmcnt(0)
	v_cvt_pk_bf16_f32 v64, v64, v65
	v_cvt_pk_bf16_f32 v65, v66, v67
	v_cvt_pk_bf16_f32 v66, v68, v69
	v_cvt_pk_bf16_f32 v67, v70, v71
	v_and_b32_e32 v64, v22, v64
	v_and_b32_e32 v65, v23, v65
	v_and_b32_e32 v66, v24, v66
	v_and_b32_e32 v67, v25, v67
	v_cvt_pk_bf16_f32 v72, v72, v73
	v_cvt_pk_bf16_f32 v73, v74, v75
	v_cvt_pk_bf16_f32 v74, v76, v77
	v_cvt_pk_bf16_f32 v75, v78, v79
	v_and_b32_e32 v72, v26, v72
	v_and_b32_e32 v73, v27, v73
	v_and_b32_e32 v74, v28, v74
	v_and_b32_e32 v75, v29, v75
	v_cvt_pk_bf16_f32 v80, v80, v81
	v_cvt_pk_bf16_f32 v81, v82, v83
	v_cvt_pk_bf16_f32 v82, v84, v85
	v_cvt_pk_bf16_f32 v83, v86, v87
	v_cvt_pk_bf16_f32 v88, v88, v89
	v_cvt_pk_bf16_f32 v89, v90, v91
	v_cvt_pk_bf16_f32 v90, v92, v93
	v_cvt_pk_bf16_f32 v91, v94, v95
	v_cvt_pk_bf16_f32 v96, v96, v97
	v_cvt_pk_bf16_f32 v97, v98, v99
	v_cvt_pk_bf16_f32 v98, v100, v101
	v_cvt_pk_bf16_f32 v99, v102, v103
	v_and_b32_e32 v96, s12, v96
	v_and_b32_e32 v97, s12, v97
	v_and_b32_e32 v98, s12, v98
	v_and_b32_e32 v99, s12, v99
	v_cvt_pk_bf16_f32 v104, v104, v105
	v_cvt_pk_bf16_f32 v105, v106, v107
	v_cvt_pk_bf16_f32 v106, v108, v109
	v_cvt_pk_bf16_f32 v107, v110, v111
	v_and_b32_e32 v104, s12, v104
	v_and_b32_e32 v105, s12, v105
	v_and_b32_e32 v106, s12, v106
	v_and_b32_e32 v107, s12, v107
	v_cvt_pk_bf16_f32 v112, v112, v113
	v_cvt_pk_bf16_f32 v113, v114, v115
	v_cvt_pk_bf16_f32 v114, v116, v117
	v_cvt_pk_bf16_f32 v115, v118, v119
	v_and_b32_e32 v112, v22, v112
	v_and_b32_e32 v113, v23, v113
	v_and_b32_e32 v114, v24, v114
	v_and_b32_e32 v115, v25, v115
	v_cvt_pk_bf16_f32 v120, v120, v121
	v_cvt_pk_bf16_f32 v121, v122, v123
	v_cvt_pk_bf16_f32 v122, v124, v125
	v_cvt_pk_bf16_f32 v123, v126, v127
	v_and_b32_e32 v120, v26, v120
	v_and_b32_e32 v121, v27, v121
	v_and_b32_e32 v122, v28, v122
	v_and_b32_e32 v123, v29, v123
	s_waitcnt lgkmcnt(0)
	s_barrier
	ds_read_b128 v[100:103], v5
	ds_read_b128 v[108:111], v5 offset:4352
	ds_read_b128 v[116:119], v5 offset:8704
	ds_read_b128 v[124:127], v5 offset:13056
	s_waitcnt lgkmcnt(0)
	v_mfma_f32_16x16x32_bf16 v[32:35], v[100:103], v[64:67], 0
	v_mfma_f32_16x16x32_bf16 v[36:39], v[108:111], v[64:67], 0
	v_mfma_f32_16x16x32_bf16 v[40:43], v[116:119], v[64:67], 0
	v_mfma_f32_16x16x32_bf16 v[44:47], v[124:127], v[64:67], 0
	v_mfma_f32_16x16x32_bf16 v[48:51], v[100:103], v[72:75], 0
	v_mfma_f32_16x16x32_bf16 v[52:55], v[108:111], v[72:75], 0
	v_mfma_f32_16x16x32_bf16 v[56:59], v[116:119], v[72:75], 0
	v_mfma_f32_16x16x32_bf16 v[60:63], v[124:127], v[72:75], 0
	v_mfma_f32_16x16x32_bf16 v[128:131], v[100:103], v[80:83], 0
	v_mfma_f32_16x16x32_bf16 v[132:135], v[108:111], v[80:83], 0
	v_mfma_f32_16x16x32_bf16 v[136:139], v[116:119], v[80:83], 0
	v_mfma_f32_16x16x32_bf16 v[140:143], v[124:127], v[80:83], 0
	v_mfma_f32_16x16x32_bf16 v[156:159], v[100:103], v[88:91], 0
	v_mfma_f32_16x16x32_bf16 v[160:163], v[108:111], v[88:91], 0
	v_mfma_f32_16x16x32_bf16 v[164:167], v[116:119], v[88:91], 0
	v_mfma_f32_16x16x32_bf16 v[168:171], v[124:127], v[88:91], 0
	ds_read_b128 v[68:71], v5 offset:64
	ds_read_b128 v[76:79], v5 offset:4416
	ds_read_b128 v[84:87], v5 offset:8768
	ds_read_b128 v[92:95], v5 offset:13120
	s_waitcnt lgkmcnt(0)
	v_mfma_f32_16x16x32_bf16 v[32:35], v[68:71], v[96:99], v[32:35]
	v_mfma_f32_16x16x32_bf16 v[36:39], v[76:79], v[96:99], v[36:39]
	v_mfma_f32_16x16x32_bf16 v[40:43], v[84:87], v[96:99], v[40:43]
	v_mfma_f32_16x16x32_bf16 v[44:47], v[92:95], v[96:99], v[44:47]
	v_mfma_f32_16x16x32_bf16 v[48:51], v[68:71], v[104:107], v[48:51]
	v_mfma_f32_16x16x32_bf16 v[52:55], v[76:79], v[104:107], v[52:55]
	v_mfma_f32_16x16x32_bf16 v[56:59], v[84:87], v[104:107], v[56:59]
	v_mfma_f32_16x16x32_bf16 v[60:63], v[92:95], v[104:107], v[60:63]
	v_mfma_f32_16x16x32_bf16 v[128:131], v[68:71], v[112:115], v[128:131]
	v_mfma_f32_16x16x32_bf16 v[132:135], v[76:79], v[112:115], v[132:135]
	v_mfma_f32_16x16x32_bf16 v[136:139], v[84:87], v[112:115], v[136:139]
	v_mfma_f32_16x16x32_bf16 v[140:143], v[92:95], v[112:115], v[140:143]
	v_mfma_f32_16x16x32_bf16 v[156:159], v[68:71], v[120:123], v[156:159]
	v_mfma_f32_16x16x32_bf16 v[160:163], v[76:79], v[120:123], v[160:163]
	v_mfma_f32_16x16x32_bf16 v[164:167], v[84:87], v[120:123], v[164:167]
	v_mfma_f32_16x16x32_bf16 v[168:171], v[92:95], v[120:123], v[168:171]
	s_cmp_eq_u32 s4, 0
	s_cbranch_scc1 .Lmixb_gate
	s_sub_u32 s10, s10, 0x8000
	s_subb_u32 s11, s11, 0
	global_load_dwordx4 v[64:67], v3, s[10:11] offset:256
	global_load_dwordx4 v[68:71], v3, s[10:11] offset:272
	s_add_u32 s10, s10, 0x2000
	s_addc_u32 s11, s11, 0
	global_load_dwordx4 v[72:75], v3, s[10:11] offset:256
	global_load_dwordx4 v[76:79], v3, s[10:11] offset:272
	s_add_u32 s10, s10, 0x2000
	s_addc_u32 s11, s11, 0
	global_load_dwordx4 v[80:83], v3, s[10:11] offset:256
	global_load_dwordx4 v[84:87], v3, s[10:11] offset:272
	global_load_dwordx4 v[96:99], v3, s[10:11] offset:384
	global_load_dwordx4 v[100:103], v3, s[10:11] offset:400
	s_add_u32 s10, s10, 0x2000
	s_addc_u32 s11, s11, 0
	global_load_dwordx4 v[88:91], v3, s[10:11] offset:256
	global_load_dwordx4 v[92:95], v3, s[10:11] offset:272
	global_load_dwordx4 v[104:107], v3, s[10:11] offset:384
	global_load_dwordx4 v[108:111], v3, s[10:11] offset:400
	s_waitcnt vmcnt(0)
	v_cvt_pk_bf16_f32 v64, v64, v65
	v_cvt_pk_bf16_f32 v65, v66, v67
	v_cvt_pk_bf16_f32 v66, v68, v69
	v_cvt_pk_bf16_f32 v67, v70, v71
	v_and_b32_e32 v64, v14, v64
	v_and_b32_e32 v65, v15, v65
	v_and_b32_e32 v66, v16, v66
	v_and_b32_e32 v67, v17, v67
	v_cvt_pk_bf16_f32 v72, v72, v73
	v_cvt_pk_bf16_f32 v73, v74, v75
	v_cvt_pk_bf16_f32 v74, v76, v77
	v_cvt_pk_bf16_f32 v75, v78, v79
	v_and_b32_e32 v72, v18, v72
	v_and_b32_e32 v73, v19, v73
	v_and_b32_e32 v74, v20, v74
	v_and_b32_e32 v75, v21, v75
	v_cvt_pk_bf16_f32 v80, v80, v81
	v_cvt_pk_bf16_f32 v81, v82, v83
	v_cvt_pk_bf16_f32 v82, v84, v85
	v_cvt_pk_bf16_f32 v83, v86, v87
	v_cvt_pk_bf16_f32 v88, v88, v89
	v_cvt_pk_bf16_f32 v89, v90, v91
	v_cvt_pk_bf16_f32 v90, v92, v93
	v_cvt_pk_bf16_f32 v91, v94, v95
	v_cvt_pk_bf16_f32 v96, v96, v97
	v_cvt_pk_bf16_f32 v97, v98, v99
	v_cvt_pk_bf16_f32 v98, v100, v101
	v_cvt_pk_bf16_f32 v99, v102, v103
	v_and_b32_e32 v96, v14, v96
	v_and_b32_e32 v97, v15, v97
	v_and_b32_e32 v98, v16, v98
	v_and_b32_e32 v99, v17, v99
	v_cvt_pk_bf16_f32 v104, v104, v105
	v_cvt_pk_bf16_f32 v105, v106, v107
	v_cvt_pk_bf16_f32 v106, v108, v109
	v_cvt_pk_bf16_f32 v107, v110, v111
	v_and_b32_e32 v104, v18, v104
	v_and_b32_e32 v105, v19, v105
	v_and_b32_e32 v106, v20, v106
	v_and_b32_e32 v107, v21, v107
	ds_read_b128 v[68:71], v5 offset:128
	ds_read_b128 v[76:79], v5 offset:4480
	ds_read_b128 v[84:87], v5 offset:8832
	ds_read_b128 v[92:95], v5 offset:13184
	ds_read_b128 v[100:103], v5 offset:192
	ds_read_b128 v[108:111], v5 offset:4544
	ds_read_b128 v[112:115], v5 offset:8896
	ds_read_b128 v[116:119], v5 offset:13248
	s_waitcnt lgkmcnt(4)
	v_mfma_f32_16x16x32_bf16 v[32:35], v[68:71], v[64:67], v[32:35]
	v_mfma_f32_16x16x32_bf16 v[36:39], v[76:79], v[64:67], v[36:39]
	v_mfma_f32_16x16x32_bf16 v[40:43], v[84:87], v[64:67], v[40:43]
	v_mfma_f32_16x16x32_bf16 v[44:47], v[92:95], v[64:67], v[44:47]
	v_mfma_f32_16x16x32_bf16 v[48:51], v[68:71], v[72:75], v[48:51]
	v_mfma_f32_16x16x32_bf16 v[52:55], v[76:79], v[72:75], v[52:55]
	v_mfma_f32_16x16x32_bf16 v[56:59], v[84:87], v[72:75], v[56:59]
	v_mfma_f32_16x16x32_bf16 v[60:63], v[92:95], v[72:75], v[60:63]
	v_mfma_f32_16x16x32_bf16 v[128:131], v[68:71], v[80:83], v[128:131]
	v_mfma_f32_16x16x32_bf16 v[132:135], v[76:79], v[80:83], v[132:135]
	v_mfma_f32_16x16x32_bf16 v[136:139], v[84:87], v[80:83], v[136:139]
	v_mfma_f32_16x16x32_bf16 v[140:143], v[92:95], v[80:83], v[140:143]
	v_mfma_f32_16x16x32_bf16 v[156:159], v[68:71], v[88:91], v[156:159]
	v_mfma_f32_16x16x32_bf16 v[160:163], v[76:79], v[88:91], v[160:163]
	v_mfma_f32_16x16x32_bf16 v[164:167], v[84:87], v[88:91], v[164:167]
	v_mfma_f32_16x16x32_bf16 v[168:171], v[92:95], v[88:91], v[168:171]
	s_waitcnt lgkmcnt(0)
	v_mfma_f32_16x16x32_bf16 v[128:131], v[100:103], v[96:99], v[128:131]
	v_mfma_f32_16x16x32_bf16 v[132:135], v[108:111], v[96:99], v[132:135]
	v_mfma_f32_16x16x32_bf16 v[136:139], v[112:115], v[96:99], v[136:139]
	v_mfma_f32_16x16x32_bf16 v[140:143], v[116:119], v[96:99], v[140:143]
	v_mfma_f32_16x16x32_bf16 v[156:159], v[100:103], v[104:107], v[156:159]
	v_mfma_f32_16x16x32_bf16 v[160:163], v[108:111], v[104:107], v[160:163]
	v_mfma_f32_16x16x32_bf16 v[164:167], v[112:115], v[104:107], v[164:167]
	v_mfma_f32_16x16x32_bf16 v[168:171], v[116:119], v[104:107], v[168:171]
.Lmixb_gate:
	s_lshl_b32 s5, s4, 6
	s_add_i32 s5, s5, s0
	s_mul_i32 s5, s5, 0x1800
	s_lshl_b32 s36, s3, 7
	s_add_i32 s5, s5, s36
	s_add_u32 s10, s66, s5
	s_addc_u32 s11, s67, 0
	global_load_dword v96, v7, s[14:15]
	global_load_dword v97, v7, s[14:15] offset:64
	global_load_dword v98, v7, s[14:15] offset:128
	global_load_dword v99, v7, s[14:15] offset:192
	global_load_dwordx2 v[64:65], v6, s[10:11] offset:1536
	global_load_dwordx2 v[66:67], v6, s[10:11] offset:1568
	global_load_dwordx2 v[68:69], v6, s[10:11] offset:1600
	global_load_dwordx2 v[70:71], v6, s[10:11] offset:1632
	s_add_u32 s10, s10, 0x18000
	s_addc_u32 s11, s11, 0
	global_load_dwordx2 v[72:73], v6, s[10:11] offset:1536
	global_load_dwordx2 v[74:75], v6, s[10:11] offset:1568
	global_load_dwordx2 v[76:77], v6, s[10:11] offset:1600
	global_load_dwordx2 v[78:79], v6, s[10:11] offset:1632
	s_add_u32 s10, s10, 0x18000
	s_addc_u32 s11, s11, 0
	global_load_dwordx2 v[80:81], v6, s[10:11] offset:1536
	global_load_dwordx2 v[82:83], v6, s[10:11] offset:1568
	global_load_dwordx2 v[84:85], v6, s[10:11] offset:1600
	global_load_dwordx2 v[86:87], v6, s[10:11] offset:1632
	s_add_u32 s10, s10, 0x18000
	s_addc_u32 s11, s11, 0
	global_load_dwordx2 v[88:89], v6, s[10:11] offset:1536
	global_load_dwordx2 v[90:91], v6, s[10:11] offset:1568
	global_load_dwordx2 v[92:93], v6, s[10:11] offset:1600
	global_load_dwordx2 v[94:95], v6, s[10:11] offset:1632
	s_sub_u32 s10, s10, 0x47000
	s_subb_u32 s11, s11, 0
	s_nop 7
	s_waitcnt vmcnt(0)
	v_add_f32_e32 v32, v96, v32
	v_add_f32_e32 v33, v96, v33
	v_add_f32_e32 v34, v96, v34
	v_add_f32_e32 v35, v96, v35
	v_lshlrev_b32_e32 v104, 16, v64
	v_and_b32_e32 v105, 0xffff0000, v64
	v_lshlrev_b32_e32 v106, 16, v65
	v_and_b32_e32 v107, 0xffff0000, v65
	v_mul_f32_e32 v32, v32, v104
	v_mul_f32_e32 v33, v33, v105
	v_mul_f32_e32 v34, v34, v106
	v_mul_f32_e32 v35, v35, v107
	v_cvt_pk_bf16_f32 v32, v32, v33
	v_cvt_pk_bf16_f32 v33, v34, v35
	global_store_dwordx2 v6, v[32:33], s[10:11] offset:512
	v_add_f32_e32 v36, v96, v36
	v_add_f32_e32 v37, v96, v37
	v_add_f32_e32 v38, v96, v38
	v_add_f32_e32 v39, v96, v39
	v_lshlrev_b32_e32 v108, 16, v66
	v_and_b32_e32 v109, 0xffff0000, v66
	v_lshlrev_b32_e32 v110, 16, v67
	v_and_b32_e32 v111, 0xffff0000, v67
	v_mul_f32_e32 v36, v36, v108
	v_mul_f32_e32 v37, v37, v109
	v_mul_f32_e32 v38, v38, v110
	v_mul_f32_e32 v39, v39, v111
	v_cvt_pk_bf16_f32 v36, v36, v37
	v_cvt_pk_bf16_f32 v37, v38, v39
	global_store_dwordx2 v6, v[36:37], s[10:11] offset:544
	v_add_f32_e32 v40, v96, v40
	v_add_f32_e32 v41, v96, v41
	v_add_f32_e32 v42, v96, v42
	v_add_f32_e32 v43, v96, v43
	v_lshlrev_b32_e32 v104, 16, v68
	v_and_b32_e32 v105, 0xffff0000, v68
	v_lshlrev_b32_e32 v106, 16, v69
	v_and_b32_e32 v107, 0xffff0000, v69
	v_mul_f32_e32 v40, v40, v104
	v_mul_f32_e32 v41, v41, v105
	v_mul_f32_e32 v42, v42, v106
	v_mul_f32_e32 v43, v43, v107
	v_cvt_pk_bf16_f32 v40, v40, v41
	v_cvt_pk_bf16_f32 v41, v42, v43
	global_store_dwordx2 v6, v[40:41], s[10:11] offset:576
	v_add_f32_e32 v44, v96, v44
	v_add_f32_e32 v45, v96, v45
	v_add_f32_e32 v46, v96, v46
	v_add_f32_e32 v47, v96, v47
	v_lshlrev_b32_e32 v108, 16, v70
	v_and_b32_e32 v109, 0xffff0000, v70
	v_lshlrev_b32_e32 v110, 16, v71
	v_and_b32_e32 v111, 0xffff0000, v71
	v_mul_f32_e32 v44, v44, v108
	v_mul_f32_e32 v45, v45, v109
	v_mul_f32_e32 v46, v46, v110
	v_mul_f32_e32 v47, v47, v111
	v_cvt_pk_bf16_f32 v44, v44, v45
	v_cvt_pk_bf16_f32 v45, v46, v47
	global_store_dwordx2 v6, v[44:45], s[10:11] offset:608
	s_add_u32 s10, s10, 0x18000
	s_addc_u32 s11, s11, 0
	v_add_f32_e32 v48, v97, v48
	v_add_f32_e32 v49, v97, v49
	v_add_f32_e32 v50, v97, v50
	v_add_f32_e32 v51, v97, v51
	v_lshlrev_b32_e32 v104, 16, v72
	v_and_b32_e32 v105, 0xffff0000, v72
	v_lshlrev_b32_e32 v106, 16, v73
	v_and_b32_e32 v107, 0xffff0000, v73
	v_mul_f32_e32 v48, v48, v104
	v_mul_f32_e32 v49, v49, v105
	v_mul_f32_e32 v50, v50, v106
	v_mul_f32_e32 v51, v51, v107
	v_cvt_pk_bf16_f32 v48, v48, v49
	v_cvt_pk_bf16_f32 v49, v50, v51
	global_store_dwordx2 v6, v[48:49], s[10:11] offset:512
	v_add_f32_e32 v52, v97, v52
	v_add_f32_e32 v53, v97, v53
	v_add_f32_e32 v54, v97, v54
	v_add_f32_e32 v55, v97, v55
	v_lshlrev_b32_e32 v108, 16, v74
	v_and_b32_e32 v109, 0xffff0000, v74
	v_lshlrev_b32_e32 v110, 16, v75
	v_and_b32_e32 v111, 0xffff0000, v75
	v_mul_f32_e32 v52, v52, v108
	v_mul_f32_e32 v53, v53, v109
	v_mul_f32_e32 v54, v54, v110
	v_mul_f32_e32 v55, v55, v111
	v_cvt_pk_bf16_f32 v52, v52, v53
	v_cvt_pk_bf16_f32 v53, v54, v55
	global_store_dwordx2 v6, v[52:53], s[10:11] offset:544
	v_add_f32_e32 v56, v97, v56
	v_add_f32_e32 v57, v97, v57
	v_add_f32_e32 v58, v97, v58
	v_add_f32_e32 v59, v97, v59
	v_lshlrev_b32_e32 v104, 16, v76
	v_and_b32_e32 v105, 0xffff0000, v76
	v_lshlrev_b32_e32 v106, 16, v77
	v_and_b32_e32 v107, 0xffff0000, v77
	v_mul_f32_e32 v56, v56, v104
	v_mul_f32_e32 v57, v57, v105
	v_mul_f32_e32 v58, v58, v106
	v_mul_f32_e32 v59, v59, v107
	v_cvt_pk_bf16_f32 v56, v56, v57
	v_cvt_pk_bf16_f32 v57, v58, v59
	global_store_dwordx2 v6, v[56:57], s[10:11] offset:576
	v_add_f32_e32 v60, v97, v60
	v_add_f32_e32 v61, v97, v61
	v_add_f32_e32 v62, v97, v62
	v_add_f32_e32 v63, v97, v63
	v_lshlrev_b32_e32 v108, 16, v78
	v_and_b32_e32 v109, 0xffff0000, v78
	v_lshlrev_b32_e32 v110, 16, v79
	v_and_b32_e32 v111, 0xffff0000, v79
	v_mul_f32_e32 v60, v60, v108
	v_mul_f32_e32 v61, v61, v109
	v_mul_f32_e32 v62, v62, v110
	v_mul_f32_e32 v63, v63, v111
	v_cvt_pk_bf16_f32 v60, v60, v61
	v_cvt_pk_bf16_f32 v61, v62, v63
	global_store_dwordx2 v6, v[60:61], s[10:11] offset:608
	s_add_u32 s10, s10, 0x18000
	s_addc_u32 s11, s11, 0
	v_add_f32_e32 v128, v98, v128
	v_add_f32_e32 v129, v98, v129
	v_add_f32_e32 v130, v98, v130
	v_add_f32_e32 v131, v98, v131
	v_lshlrev_b32_e32 v104, 16, v80
	v_and_b32_e32 v105, 0xffff0000, v80
	v_lshlrev_b32_e32 v106, 16, v81
	v_and_b32_e32 v107, 0xffff0000, v81
	v_mul_f32_e32 v128, v128, v104
	v_mul_f32_e32 v129, v129, v105
	v_mul_f32_e32 v130, v130, v106
	v_mul_f32_e32 v131, v131, v107
	v_cvt_pk_bf16_f32 v128, v128, v129
	v_cvt_pk_bf16_f32 v129, v130, v131
	global_store_dwordx2 v6, v[128:129], s[10:11] offset:512
	v_add_f32_e32 v132, v98, v132
	v_add_f32_e32 v133, v98, v133
	v_add_f32_e32 v134, v98, v134
	v_add_f32_e32 v135, v98, v135
	v_lshlrev_b32_e32 v108, 16, v82
	v_and_b32_e32 v109, 0xffff0000, v82
	v_lshlrev_b32_e32 v110, 16, v83
	v_and_b32_e32 v111, 0xffff0000, v83
	v_mul_f32_e32 v132, v132, v108
	v_mul_f32_e32 v133, v133, v109
	v_mul_f32_e32 v134, v134, v110
	v_mul_f32_e32 v135, v135, v111
	v_cvt_pk_bf16_f32 v132, v132, v133
	v_cvt_pk_bf16_f32 v133, v134, v135
	global_store_dwordx2 v6, v[132:133], s[10:11] offset:544
	v_add_f32_e32 v136, v98, v136
	v_add_f32_e32 v137, v98, v137
	v_add_f32_e32 v138, v98, v138
	v_add_f32_e32 v139, v98, v139
	v_lshlrev_b32_e32 v104, 16, v84
	v_and_b32_e32 v105, 0xffff0000, v84
	v_lshlrev_b32_e32 v106, 16, v85
	v_and_b32_e32 v107, 0xffff0000, v85
	v_mul_f32_e32 v136, v136, v104
	v_mul_f32_e32 v137, v137, v105
	v_mul_f32_e32 v138, v138, v106
	v_mul_f32_e32 v139, v139, v107
	v_cvt_pk_bf16_f32 v136, v136, v137
	v_cvt_pk_bf16_f32 v137, v138, v139
	global_store_dwordx2 v6, v[136:137], s[10:11] offset:576
	v_add_f32_e32 v140, v98, v140
	v_add_f32_e32 v141, v98, v141
	v_add_f32_e32 v142, v98, v142
	v_add_f32_e32 v143, v98, v143
	v_lshlrev_b32_e32 v108, 16, v86
	v_and_b32_e32 v109, 0xffff0000, v86
	v_lshlrev_b32_e32 v110, 16, v87
	v_and_b32_e32 v111, 0xffff0000, v87
	v_mul_f32_e32 v140, v140, v108
	v_mul_f32_e32 v141, v141, v109
	v_mul_f32_e32 v142, v142, v110
	v_mul_f32_e32 v143, v143, v111
	v_cvt_pk_bf16_f32 v140, v140, v141
	v_cvt_pk_bf16_f32 v141, v142, v143
	global_store_dwordx2 v6, v[140:141], s[10:11] offset:608
	s_add_u32 s10, s10, 0x18000
	s_addc_u32 s11, s11, 0
	v_add_f32_e32 v156, v99, v156
	v_add_f32_e32 v157, v99, v157
	v_add_f32_e32 v158, v99, v158
	v_add_f32_e32 v159, v99, v159
	v_lshlrev_b32_e32 v104, 16, v88
	v_and_b32_e32 v105, 0xffff0000, v88
	v_lshlrev_b32_e32 v106, 16, v89
	v_and_b32_e32 v107, 0xffff0000, v89
	v_mul_f32_e32 v156, v156, v104
	v_mul_f32_e32 v157, v157, v105
	v_mul_f32_e32 v158, v158, v106
	v_mul_f32_e32 v159, v159, v107
	v_cvt_pk_bf16_f32 v156, v156, v157
	v_cvt_pk_bf16_f32 v157, v158, v159
	global_store_dwordx2 v6, v[156:157], s[10:11] offset:512
	v_add_f32_e32 v160, v99, v160
	v_add_f32_e32 v161, v99, v161
	v_add_f32_e32 v162, v99, v162
	v_add_f32_e32 v163, v99, v163
	v_lshlrev_b32_e32 v108, 16, v90
	v_and_b32_e32 v109, 0xffff0000, v90
	v_lshlrev_b32_e32 v110, 16, v91
	v_and_b32_e32 v111, 0xffff0000, v91
	v_mul_f32_e32 v160, v160, v108
	v_mul_f32_e32 v161, v161, v109
	v_mul_f32_e32 v162, v162, v110
	v_mul_f32_e32 v163, v163, v111
	v_cvt_pk_bf16_f32 v160, v160, v161
	v_cvt_pk_bf16_f32 v161, v162, v163
	global_store_dwordx2 v6, v[160:161], s[10:11] offset:544
	v_add_f32_e32 v164, v99, v164
	v_add_f32_e32 v165, v99, v165
	v_add_f32_e32 v166, v99, v166
	v_add_f32_e32 v167, v99, v167
	v_lshlrev_b32_e32 v104, 16, v92
	v_and_b32_e32 v105, 0xffff0000, v92
	v_lshlrev_b32_e32 v106, 16, v93
	v_and_b32_e32 v107, 0xffff0000, v93
	v_mul_f32_e32 v164, v164, v104
	v_mul_f32_e32 v165, v165, v105
	v_mul_f32_e32 v166, v166, v106
	v_mul_f32_e32 v167, v167, v107
	v_cvt_pk_bf16_f32 v164, v164, v165
	v_cvt_pk_bf16_f32 v165, v166, v167
	global_store_dwordx2 v6, v[164:165], s[10:11] offset:576
	v_add_f32_e32 v168, v99, v168
	v_add_f32_e32 v169, v99, v169
	v_add_f32_e32 v170, v99, v170
	v_add_f32_e32 v171, v99, v171
	v_lshlrev_b32_e32 v108, 16, v94
	v_and_b32_e32 v109, 0xffff0000, v94
	v_lshlrev_b32_e32 v110, 16, v95
	v_and_b32_e32 v111, 0xffff0000, v95
	v_mul_f32_e32 v168, v168, v108
	v_mul_f32_e32 v169, v169, v109
	v_mul_f32_e32 v170, v170, v110
	v_mul_f32_e32 v171, v171, v111
	v_cvt_pk_bf16_f32 v168, v168, v169
	v_cvt_pk_bf16_f32 v169, v170, v171
	global_store_dwordx2 v6, v[168:169], s[10:11] offset:608
	v_readlane_b32 s8, v255, 40
	v_readlane_b32 s9, v255, 41
	v_readlane_b32 s10, v255, 42
	v_readlane_b32 s11, v255, 43
	v_readlane_b32 s12, v255, 44
	v_readlane_b32 s13, v255, 45
	v_readlane_b32 s14, v255, 46
	v_readlane_b32 s15, v255, 47
	s_mov_b64 s[4:5], 0
	s_mov_b64 s[2:3], -1
	s_barrier
	s_branch .LBB0_485
